# WIN f-gate epilogue: log argument 1+exp(-|d|) lies in [1,2], so the denormal rescale and finite check around each log are removed (bit-exact)
# speedup vs baseline: 1.0002x; 1.0002x over previous
.LBB0_427:
	v_lshlrev_b32_e32 v166, 3, v100
	v_lshlrev_b32_e32 v208, 1, v100
	global_load_dwordx4 v[84:87], v166, s[14:15] offset:48
	global_load_dwordx4 v[88:91], v166, s[14:15] offset:32
	global_load_dwordx4 v[96:99], v166, s[14:15] offset:16
	global_load_dwordx4 v[100:103], v166, s[14:15]
	v_ashrrev_i32_e32 v159, 31, v158
	v_lshlrev_b64 v[156:157], 11, v[158:159]
	v_max_f32_e32 v159, v140, v140
	v_mul_f32_e64 v140, |v140|, s43
	v_exp_f32_e32 v140, v140
	v_min_f32_e32 v159, 0, v159
	v_lshl_add_u64 v[160:161], s[18:19], 0, v[156:157]
	v_lshl_add_u64 v[160:161], v[160:161], 0, v[208:209]
	v_add_f32_e32 v140, 1.0, v140
	v_cmp_gt_f32_e32 vcc, s3, v140
	s_mov_b64 s[4:5], 0x48000
	s_waitcnt vmcnt(0)
	v_max_f32_e32 v169, v86, v86
	v_cndmask_b32_e64 v167, 0, 32, vcc
	v_ldexp_f32 v140, v140, v167
	v_log_f32_e32 v140, v140
	s_nop 0
	v_mul_f32_e32 v167, 0x3f317217, v140
	v_fma_f32 v167, v140, s44, -v167
	v_fmac_f32_e32 v167, 0x3377d1cf, v140
	v_fmac_f32_e32 v167, 0x3f317217, v140
	v_cmp_lt_f32_e64 s[10:11], |v140|, s45
	s_nop 1
	v_cndmask_b32_e64 v140, v140, v167, s[10:11]
	v_cndmask_b32_e32 v167, 0, v242, vcc
	v_sub_f32_e32 v140, v140, v167
	v_sub_f32_e32 v140, v159, v140
	v_add_f32_e32 v159, v140, v101
	v_max_f32_e32 v140, v100, v100
	v_max_f32_e32 v167, v140, v159
	v_sub_f32_e32 v159, v100, v159
	v_mul_f32_e64 v159, |v159|, s43
	v_exp_f32_e32 v159, v159
	s_nop 0
	v_add_f32_e32 v159, 1.0, v159
	v_log_f32_e32 v159, v159
	s_nop 0
	v_mul_f32_e32 v168, 0x3f317217, v159
	v_fma_f32 v168, v159, s44, -v168
	v_fmac_f32_e32 v168, 0x3377d1cf, v159
	v_fmac_f32_e32 v168, 0x3f317217, v159
	v_mov_b32_e32 v159, v168
	v_add_f32_e32 v170, v167, v159
	v_max_f32_e32 v159, v141, v141
	v_mul_f32_e64 v141, |v141|, s43
	v_exp_f32_e32 v141, v141
	v_min_f32_e32 v159, 0, v159
	v_add_f32_e32 v141, 1.0, v141
	v_log_f32_e32 v141, v141
	s_nop 0
	v_mul_f32_e32 v167, 0x3f317217, v141
	v_fma_f32 v167, v141, s44, -v167
	v_fmac_f32_e32 v167, 0x3377d1cf, v141
	v_fmac_f32_e32 v167, 0x3f317217, v141
	v_mov_b32_e32 v141, v167
	v_sub_f32_e32 v141, v159, v141
	v_add_f32_e32 v159, v141, v103
	v_max_f32_e32 v141, v102, v102
	v_max_f32_e32 v167, v141, v159
	v_sub_f32_e32 v159, v102, v159
	v_mul_f32_e64 v159, |v159|, s43
	v_exp_f32_e32 v159, v159
	s_nop 0
	v_add_f32_e32 v159, 1.0, v159
	v_log_f32_e32 v159, v159
	s_nop 0
	v_mul_f32_e32 v168, 0x3f317217, v159
	v_fma_f32 v168, v159, s44, -v168
	v_fmac_f32_e32 v168, 0x3377d1cf, v159
	v_fmac_f32_e32 v168, 0x3f317217, v159
	v_mov_b32_e32 v159, v168
	v_add_f32_e32 v171, v167, v159
	v_max_f32_e32 v159, v142, v142
	v_mul_f32_e64 v142, |v142|, s43
	v_exp_f32_e32 v142, v142
	v_min_f32_e32 v159, 0, v159
	v_add_f32_e32 v142, 1.0, v142
	v_log_f32_e32 v142, v142
	s_nop 0
	v_mul_f32_e32 v167, 0x3f317217, v142
	v_fma_f32 v167, v142, s44, -v167
	v_fmac_f32_e32 v167, 0x3377d1cf, v142
	v_fmac_f32_e32 v167, 0x3f317217, v142
	v_mov_b32_e32 v142, v167
	v_sub_f32_e32 v142, v159, v142
	v_add_f32_e32 v159, v142, v97
	v_max_f32_e32 v142, v96, v96
	v_max_f32_e32 v167, v142, v159
	v_sub_f32_e32 v159, v96, v159
	v_mul_f32_e64 v159, |v159|, s43
	v_exp_f32_e32 v159, v159
	s_nop 0
	v_add_f32_e32 v159, 1.0, v159
	v_log_f32_e32 v159, v159
	s_nop 0
	v_mul_f32_e32 v168, 0x3f317217, v159
	v_fma_f32 v168, v159, s44, -v168
	v_fmac_f32_e32 v168, 0x3377d1cf, v159
	v_fmac_f32_e32 v168, 0x3f317217, v159
	v_mov_b32_e32 v159, v168
	v_add_f32_e32 v172, v167, v159
	v_max_f32_e32 v159, v143, v143
	v_mul_f32_e64 v143, |v143|, s43
	v_exp_f32_e32 v143, v143
	v_min_f32_e32 v159, 0, v159
	v_add_f32_e32 v143, 1.0, v143
	v_log_f32_e32 v143, v143
	s_nop 0
	v_mul_f32_e32 v167, 0x3f317217, v143
	v_fma_f32 v167, v143, s44, -v167
	v_fmac_f32_e32 v167, 0x3377d1cf, v143
	v_fmac_f32_e32 v167, 0x3f317217, v143
	v_mov_b32_e32 v143, v167
	v_sub_f32_e32 v143, v159, v143
	v_add_f32_e32 v159, v143, v99
	v_max_f32_e32 v143, v98, v98
	v_max_f32_e32 v167, v143, v159
	v_sub_f32_e32 v159, v98, v159
	v_mul_f32_e64 v159, |v159|, s43
	v_exp_f32_e32 v159, v159
	s_nop 0
	v_add_f32_e32 v159, 1.0, v159
	v_log_f32_e32 v159, v159
	s_nop 0
	v_mul_f32_e32 v168, 0x3f317217, v159
	v_fma_f32 v168, v159, s44, -v168
	v_fmac_f32_e32 v168, 0x3377d1cf, v159
	v_fmac_f32_e32 v168, 0x3f317217, v159
	v_mov_b32_e32 v159, v168
	v_add_f32_e32 v173, v167, v159
	v_max_f32_e32 v159, v136, v136
	v_mul_f32_e64 v136, |v136|, s43
	v_exp_f32_e32 v136, v136
	v_min_f32_e32 v159, 0, v159
	v_add_f32_e32 v136, 1.0, v136
	v_log_f32_e32 v136, v136
	s_nop 0
	v_mul_f32_e32 v167, 0x3f317217, v136
	v_fma_f32 v167, v136, s44, -v167
	v_fmac_f32_e32 v167, 0x3377d1cf, v136
	v_fmac_f32_e32 v167, 0x3f317217, v136
	v_mov_b32_e32 v136, v167
	v_sub_f32_e32 v136, v159, v136
	v_add_f32_e32 v136, v136, v89
	v_max_f32_e32 v159, v88, v88
	v_max_f32_e32 v167, v159, v136
	v_sub_f32_e32 v136, v88, v136
	v_mul_f32_e64 v136, |v136|, s43
	v_exp_f32_e32 v136, v136
	s_nop 0
	v_add_f32_e32 v136, 1.0, v136
	v_log_f32_e32 v136, v136
	s_nop 0
	v_mul_f32_e32 v168, 0x3f317217, v136
	v_fma_f32 v168, v136, s44, -v168
	v_fmac_f32_e32 v168, 0x3377d1cf, v136
	v_fmac_f32_e32 v168, 0x3f317217, v136
	v_mov_b32_e32 v136, v168
	v_add_f32_e32 v174, v167, v136
	v_max_f32_e32 v136, v137, v137
	v_mul_f32_e64 v137, |v137|, s43
	v_exp_f32_e32 v137, v137
	v_min_f32_e32 v136, 0, v136
	v_add_f32_e32 v137, 1.0, v137
	v_log_f32_e32 v137, v137
	s_nop 0
	v_mul_f32_e32 v167, 0x3f317217, v137
	v_fma_f32 v167, v137, s44, -v167
	v_fmac_f32_e32 v167, 0x3377d1cf, v137
	v_fmac_f32_e32 v167, 0x3f317217, v137
	v_mov_b32_e32 v137, v167
	v_sub_f32_e32 v136, v136, v137
	v_add_f32_e32 v136, v136, v91
	v_max_f32_e32 v167, v90, v90
	v_max_f32_e32 v137, v167, v136
	v_sub_f32_e32 v136, v90, v136
	v_mul_f32_e64 v136, |v136|, s43
	v_exp_f32_e32 v136, v136
	s_nop 0
	v_add_f32_e32 v136, 1.0, v136
	v_log_f32_e32 v136, v136
	s_nop 0
	v_mul_f32_e32 v168, 0x3f317217, v136
	v_fma_f32 v168, v136, s44, -v168
	v_fmac_f32_e32 v168, 0x3377d1cf, v136
	v_fmac_f32_e32 v168, 0x3f317217, v136
	v_mov_b32_e32 v136, v168
	v_add_f32_e32 v175, v137, v136
	v_mul_f32_e64 v137, |v138|, s43
	v_exp_f32_e32 v137, v137
	v_max_f32_e32 v136, v138, v138
	v_min_f32_e32 v136, 0, v136
	v_max_f32_e32 v168, v84, v84
	v_add_f32_e32 v137, 1.0, v137
	v_log_f32_e32 v137, v137
	s_nop 0
	v_mul_f32_e32 v138, 0x3f317217, v137
	v_fma_f32 v138, v137, s44, -v138
	v_fmac_f32_e32 v138, 0x3377d1cf, v137
	v_fmac_f32_e32 v138, 0x3f317217, v137
	v_mov_b32_e32 v137, v138
	v_sub_f32_e32 v136, v136, v137
	v_add_f32_e32 v136, v136, v85
	v_max_f32_e32 v137, v168, v136
	v_sub_f32_e32 v136, v84, v136
	v_mul_f32_e64 v136, |v136|, s43
	v_exp_f32_e32 v136, v136
	s_nop 0
	v_add_f32_e32 v136, 1.0, v136
	v_log_f32_e32 v136, v136
	s_nop 0
	v_mul_f32_e32 v138, 0x3f317217, v136
	v_fma_f32 v138, v136, s44, -v138
	v_fmac_f32_e32 v138, 0x3377d1cf, v136
	v_fmac_f32_e32 v138, 0x3f317217, v136
	v_mov_b32_e32 v136, v138
	v_add_f32_e32 v176, v137, v136
	v_mul_f32_e64 v137, |v139|, s43
	v_exp_f32_e32 v137, v137
	v_max_f32_e32 v136, v139, v139
	v_min_f32_e32 v136, 0, v136
	v_add_f32_e32 v137, 1.0, v137
	v_log_f32_e32 v137, v137
	s_nop 0
	v_mul_f32_e32 v138, 0x3f317217, v137
	v_fma_f32 v138, v137, s44, -v138
	v_fmac_f32_e32 v138, 0x3377d1cf, v137
	v_fmac_f32_e32 v138, 0x3f317217, v137
	v_mov_b32_e32 v137, v138
	v_sub_f32_e32 v136, v136, v137
	v_add_f32_e32 v136, v136, v87
	v_max_f32_e32 v137, v169, v136
	v_sub_f32_e32 v136, v86, v136
	v_mul_f32_e64 v136, |v136|, s43
	v_exp_f32_e32 v136, v136
	s_nop 0
	v_add_f32_e32 v136, 1.0, v136
	v_log_f32_e32 v136, v136
	s_nop 0
	v_mul_f32_e32 v138, 0x3f317217, v136
	v_fma_f32 v138, v136, s44, -v138
	v_fmac_f32_e32 v138, 0x3377d1cf, v136
	v_fmac_f32_e32 v138, 0x3f317217, v136
	v_mov_b32_e32 v136, v138
	v_add_f32_e32 v139, v137, v136
	v_cvt_pk_f16_f32 v136, v170, v171
	v_cvt_pk_f16_f32 v137, v172, v173
	v_cvt_pk_f16_f32 v138, v174, v175
	v_cvt_pk_f16_f32 v139, v176, v139
	global_store_dwordx4 v[160:161], v[136:139], off
	v_max_f32_e32 v160, v132, v132
	v_mul_f32_e64 v132, |v132|, s43
	v_exp_f32_e32 v132, v132
	v_min_f32_e32 v160, 0, v160
	v_or_b32_e32 v136, 16, v158
	v_ashrrev_i32_e32 v137, 31, v136
	v_add_f32_e32 v132, 1.0, v132
	v_cmp_gt_f32_e32 vcc, s3, v132
	v_lshlrev_b64 v[136:137], 11, v[136:137]
	v_lshl_add_u64 v[138:139], s[18:19], 0, v[136:137]
	v_cndmask_b32_e64 v161, 0, 32, vcc
	v_ldexp_f32 v132, v132, v161
	v_log_f32_e32 v132, v132
	v_lshl_add_u64 v[138:139], v[138:139], 0, v[208:209]
	v_mul_f32_e32 v161, 0x3f317217, v132
	v_fma_f32 v161, v132, s44, -v161
	v_fmac_f32_e32 v161, 0x3377d1cf, v132
	v_fmac_f32_e32 v161, 0x3f317217, v132
	v_cmp_lt_f32_e64 s[10:11], |v132|, s45
	s_nop 1
	v_cndmask_b32_e64 v132, v132, v161, s[10:11]
	v_cndmask_b32_e32 v161, 0, v242, vcc
	v_sub_f32_e32 v132, v132, v161
	v_sub_f32_e32 v132, v160, v132
	v_add_f32_e32 v132, v132, v101
	v_max_f32_e32 v160, v140, v132
	v_sub_f32_e32 v132, v100, v132
	v_mul_f32_e64 v132, |v132|, s43
	v_exp_f32_e32 v132, v132
	s_nop 0
	v_add_f32_e32 v132, 1.0, v132
	v_log_f32_e32 v132, v132
	s_nop 0
	v_mul_f32_e32 v161, 0x3f317217, v132
	v_fma_f32 v161, v132, s44, -v161
	v_fmac_f32_e32 v161, 0x3377d1cf, v132
	v_fmac_f32_e32 v161, 0x3f317217, v132
	v_mov_b32_e32 v132, v161
	v_add_f32_e32 v132, v160, v132
	v_max_f32_e32 v160, v133, v133
	v_mul_f32_e64 v133, |v133|, s43
	v_exp_f32_e32 v133, v133
	v_min_f32_e32 v160, 0, v160
	v_add_f32_e32 v133, 1.0, v133
	v_log_f32_e32 v133, v133
	s_nop 0
	v_mul_f32_e32 v161, 0x3f317217, v133
	v_fma_f32 v161, v133, s44, -v161
	v_fmac_f32_e32 v161, 0x3377d1cf, v133
	v_fmac_f32_e32 v161, 0x3f317217, v133
	v_mov_b32_e32 v133, v161
	v_sub_f32_e32 v133, v160, v133
	v_add_f32_e32 v133, v133, v103
	v_max_f32_e32 v160, v141, v133
	v_sub_f32_e32 v133, v102, v133
	v_mul_f32_e64 v133, |v133|, s43
	v_exp_f32_e32 v133, v133
	s_nop 0
	v_add_f32_e32 v133, 1.0, v133
	v_log_f32_e32 v133, v133
	s_nop 0
	v_mul_f32_e32 v161, 0x3f317217, v133
	v_fma_f32 v161, v133, s44, -v161
	v_fmac_f32_e32 v161, 0x3377d1cf, v133
	v_fmac_f32_e32 v161, 0x3f317217, v133
	v_mov_b32_e32 v133, v161
	v_add_f32_e32 v133, v160, v133
	v_max_f32_e32 v160, v134, v134
	v_mul_f32_e64 v134, |v134|, s43
	v_exp_f32_e32 v134, v134
	v_min_f32_e32 v160, 0, v160
	v_add_f32_e32 v134, 1.0, v134
	v_log_f32_e32 v134, v134
	s_nop 0
	v_mul_f32_e32 v161, 0x3f317217, v134
	v_fma_f32 v161, v134, s44, -v161
	v_fmac_f32_e32 v161, 0x3377d1cf, v134
	v_fmac_f32_e32 v161, 0x3f317217, v134
	v_mov_b32_e32 v134, v161
	v_sub_f32_e32 v134, v160, v134
	v_add_f32_e32 v134, v134, v97
	v_max_f32_e32 v160, v142, v134
	v_sub_f32_e32 v134, v96, v134
	v_mul_f32_e64 v134, |v134|, s43
	v_exp_f32_e32 v134, v134
	s_nop 0
	v_add_f32_e32 v134, 1.0, v134
	v_log_f32_e32 v134, v134
	s_nop 0
	v_mul_f32_e32 v161, 0x3f317217, v134
	v_fma_f32 v161, v134, s44, -v161
	v_fmac_f32_e32 v161, 0x3377d1cf, v134
	v_fmac_f32_e32 v161, 0x3f317217, v134
	v_mov_b32_e32 v134, v161
	v_add_f32_e32 v134, v160, v134
	v_max_f32_e32 v160, v135, v135
	v_mul_f32_e64 v135, |v135|, s43
	v_exp_f32_e32 v135, v135
	v_min_f32_e32 v160, 0, v160
	v_add_f32_e32 v135, 1.0, v135
	v_log_f32_e32 v135, v135
	s_nop 0
	v_mul_f32_e32 v161, 0x3f317217, v135
	v_fma_f32 v161, v135, s44, -v161
	v_fmac_f32_e32 v161, 0x3377d1cf, v135
	v_fmac_f32_e32 v161, 0x3f317217, v135
	v_mov_b32_e32 v135, v161
	v_sub_f32_e32 v135, v160, v135
	v_add_f32_e32 v135, v135, v99
	v_max_f32_e32 v160, v143, v135
	v_sub_f32_e32 v135, v98, v135
	v_mul_f32_e64 v135, |v135|, s43
	v_exp_f32_e32 v135, v135
	s_nop 0
	v_add_f32_e32 v135, 1.0, v135
	v_log_f32_e32 v135, v135
	s_nop 0
	v_mul_f32_e32 v161, 0x3f317217, v135
	v_fma_f32 v161, v135, s44, -v161
	v_fmac_f32_e32 v161, 0x3377d1cf, v135
	v_fmac_f32_e32 v161, 0x3f317217, v135
	v_mov_b32_e32 v135, v161
	v_add_f32_e32 v135, v160, v135
	v_max_f32_e32 v160, v128, v128
	v_mul_f32_e64 v128, |v128|, s43
	v_exp_f32_e32 v128, v128
	v_min_f32_e32 v160, 0, v160
	v_add_f32_e32 v128, 1.0, v128
	v_log_f32_e32 v128, v128
	s_nop 0
	v_mul_f32_e32 v161, 0x3f317217, v128
	v_fma_f32 v161, v128, s44, -v161
	v_fmac_f32_e32 v161, 0x3377d1cf, v128
	v_fmac_f32_e32 v161, 0x3f317217, v128
	v_mov_b32_e32 v128, v161
	v_sub_f32_e32 v128, v160, v128
	v_add_f32_e32 v128, v128, v89
	v_max_f32_e32 v160, v159, v128
	v_sub_f32_e32 v128, v88, v128
	v_mul_f32_e64 v128, |v128|, s43
	v_exp_f32_e32 v128, v128
	s_nop 0
	v_add_f32_e32 v128, 1.0, v128
	v_log_f32_e32 v128, v128
	s_nop 0
	v_mul_f32_e32 v161, 0x3f317217, v128
	v_fma_f32 v161, v128, s44, -v161
	v_fmac_f32_e32 v161, 0x3377d1cf, v128
	v_fmac_f32_e32 v161, 0x3f317217, v128
	v_mov_b32_e32 v128, v161
	v_add_f32_e32 v160, v160, v128
	v_max_f32_e32 v128, v129, v129
	v_mul_f32_e64 v129, |v129|, s43
	v_exp_f32_e32 v129, v129
	v_min_f32_e32 v128, 0, v128
	v_add_f32_e32 v129, 1.0, v129
	v_log_f32_e32 v129, v129
	s_nop 0
	v_mul_f32_e32 v161, 0x3f317217, v129
	v_fma_f32 v161, v129, s44, -v161
	v_fmac_f32_e32 v161, 0x3377d1cf, v129
	v_fmac_f32_e32 v161, 0x3f317217, v129
	v_mov_b32_e32 v129, v161
	v_sub_f32_e32 v128, v128, v129
	v_add_f32_e32 v128, v128, v91
	v_max_f32_e32 v129, v167, v128
	v_sub_f32_e32 v128, v90, v128
	v_mul_f32_e64 v128, |v128|, s43
	v_exp_f32_e32 v128, v128
	s_nop 0
	v_add_f32_e32 v128, 1.0, v128
	v_log_f32_e32 v128, v128
	s_nop 0
	v_mul_f32_e32 v161, 0x3f317217, v128
	v_fma_f32 v161, v128, s44, -v161
	v_fmac_f32_e32 v161, 0x3377d1cf, v128
	v_fmac_f32_e32 v161, 0x3f317217, v128
	v_mov_b32_e32 v128, v161
	v_add_f32_e32 v161, v129, v128
	v_mul_f32_e64 v129, |v130|, s43
	v_exp_f32_e32 v129, v129
	v_max_f32_e32 v128, v130, v130
	v_min_f32_e32 v128, 0, v128
	v_add_f32_e32 v129, 1.0, v129
	v_log_f32_e32 v129, v129
	s_nop 0
	v_mul_f32_e32 v130, 0x3f317217, v129
	v_fma_f32 v130, v129, s44, -v130
	v_fmac_f32_e32 v130, 0x3377d1cf, v129
	v_fmac_f32_e32 v130, 0x3f317217, v129
	v_mov_b32_e32 v129, v130
	v_sub_f32_e32 v128, v128, v129
	v_add_f32_e32 v128, v128, v85
	v_max_f32_e32 v129, v168, v128
	v_sub_f32_e32 v128, v84, v128
	v_mul_f32_e64 v128, |v128|, s43
	v_exp_f32_e32 v128, v128
	s_nop 0
	v_add_f32_e32 v128, 1.0, v128
	v_log_f32_e32 v128, v128
	s_nop 0
	v_mul_f32_e32 v130, 0x3f317217, v128
	v_fma_f32 v130, v128, s44, -v130
	v_fmac_f32_e32 v130, 0x3377d1cf, v128
	v_fmac_f32_e32 v130, 0x3f317217, v128
	v_mov_b32_e32 v128, v130
	v_add_f32_e32 v170, v129, v128
	v_mul_f32_e64 v129, |v131|, s43
	v_exp_f32_e32 v129, v129
	v_max_f32_e32 v128, v131, v131
	v_min_f32_e32 v128, 0, v128
	v_add_f32_e32 v129, 1.0, v129
	v_log_f32_e32 v129, v129
	s_nop 0
	v_mul_f32_e32 v130, 0x3f317217, v129
	v_fma_f32 v130, v129, s44, -v130
	v_fmac_f32_e32 v130, 0x3377d1cf, v129
	v_fmac_f32_e32 v130, 0x3f317217, v129
	v_mov_b32_e32 v129, v130
	v_sub_f32_e32 v128, v128, v129
	v_add_f32_e32 v128, v128, v87
	v_max_f32_e32 v129, v169, v128
	v_sub_f32_e32 v128, v86, v128
	v_mul_f32_e64 v128, |v128|, s43
	v_exp_f32_e32 v128, v128
	s_nop 0
	v_add_f32_e32 v128, 1.0, v128
	v_log_f32_e32 v128, v128
	s_nop 0
	v_mul_f32_e32 v130, 0x3f317217, v128
	v_fma_f32 v130, v128, s44, -v130
	v_fmac_f32_e32 v130, 0x3377d1cf, v128
	v_fmac_f32_e32 v130, 0x3f317217, v128
	v_mov_b32_e32 v128, v130
	v_add_f32_e32 v131, v129, v128
	v_cvt_pk_f16_f32 v128, v132, v133
	v_max_f32_e32 v132, v124, v124
	v_mul_f32_e64 v124, |v124|, s43
	v_exp_f32_e32 v124, v124
	v_min_f32_e32 v132, 0, v132
	v_cvt_pk_f16_f32 v129, v134, v135
	v_cvt_pk_f16_f32 v130, v160, v161
	v_add_f32_e32 v124, 1.0, v124
	v_cmp_gt_f32_e32 vcc, s3, v124
	v_cvt_pk_f16_f32 v131, v170, v131
	global_store_dwordx4 v[138:139], v[128:131], off
	v_cndmask_b32_e64 v133, 0, 32, vcc
	v_ldexp_f32 v124, v124, v133
	v_log_f32_e32 v124, v124
	v_or_b32_e32 v128, 32, v158
	v_ashrrev_i32_e32 v129, 31, v128
	v_lshlrev_b64 v[128:129], 11, v[128:129]
	v_mul_f32_e32 v133, 0x3f317217, v124
	v_fma_f32 v133, v124, s44, -v133
	v_fmac_f32_e32 v133, 0x3377d1cf, v124
	v_fmac_f32_e32 v133, 0x3f317217, v124
	v_cmp_lt_f32_e64 s[10:11], |v124|, s45
	v_lshl_add_u64 v[130:131], s[18:19], 0, v[128:129]
	v_lshl_add_u64 v[130:131], v[130:131], 0, v[208:209]
	v_cndmask_b32_e64 v124, v124, v133, s[10:11]
	v_cndmask_b32_e32 v133, 0, v242, vcc
	v_sub_f32_e32 v124, v124, v133
	v_sub_f32_e32 v124, v132, v124
	v_add_f32_e32 v124, v124, v101
	v_max_f32_e32 v132, v140, v124
	v_sub_f32_e32 v124, v100, v124
	v_mul_f32_e64 v124, |v124|, s43
	v_exp_f32_e32 v124, v124
	s_nop 0
	v_add_f32_e32 v124, 1.0, v124
	v_log_f32_e32 v124, v124
	s_nop 0
	v_mul_f32_e32 v133, 0x3f317217, v124
	v_fma_f32 v133, v124, s44, -v133
	v_fmac_f32_e32 v133, 0x3377d1cf, v124
	v_fmac_f32_e32 v133, 0x3f317217, v124
	v_mov_b32_e32 v124, v133
	v_add_f32_e32 v124, v132, v124
	v_max_f32_e32 v132, v125, v125
	v_mul_f32_e64 v125, |v125|, s43
	v_exp_f32_e32 v125, v125
	v_min_f32_e32 v132, 0, v132
	v_add_f32_e32 v125, 1.0, v125
	v_log_f32_e32 v125, v125
	s_nop 0
	v_mul_f32_e32 v133, 0x3f317217, v125
	v_fma_f32 v133, v125, s44, -v133
	v_fmac_f32_e32 v133, 0x3377d1cf, v125
	v_fmac_f32_e32 v133, 0x3f317217, v125
	v_mov_b32_e32 v125, v133
	v_sub_f32_e32 v125, v132, v125
	v_add_f32_e32 v125, v125, v103
	v_max_f32_e32 v132, v141, v125
	v_sub_f32_e32 v125, v102, v125
	v_mul_f32_e64 v125, |v125|, s43
	v_exp_f32_e32 v125, v125
	s_nop 0
	v_add_f32_e32 v125, 1.0, v125
	v_log_f32_e32 v125, v125
	s_nop 0
	v_mul_f32_e32 v133, 0x3f317217, v125
	v_fma_f32 v133, v125, s44, -v133
	v_fmac_f32_e32 v133, 0x3377d1cf, v125
	v_fmac_f32_e32 v133, 0x3f317217, v125
	v_mov_b32_e32 v125, v133
	v_add_f32_e32 v125, v132, v125
	v_max_f32_e32 v132, v126, v126
	v_mul_f32_e64 v126, |v126|, s43
	v_exp_f32_e32 v126, v126
	v_min_f32_e32 v132, 0, v132
	v_add_f32_e32 v126, 1.0, v126
	v_log_f32_e32 v126, v126
	s_nop 0
	v_mul_f32_e32 v133, 0x3f317217, v126
	v_fma_f32 v133, v126, s44, -v133
	v_fmac_f32_e32 v133, 0x3377d1cf, v126
	v_fmac_f32_e32 v133, 0x3f317217, v126
	v_mov_b32_e32 v126, v133
	v_sub_f32_e32 v126, v132, v126
	v_add_f32_e32 v126, v126, v97
	v_max_f32_e32 v132, v142, v126
	v_sub_f32_e32 v126, v96, v126
	v_mul_f32_e64 v126, |v126|, s43
	v_exp_f32_e32 v126, v126
	s_nop 0
	v_add_f32_e32 v126, 1.0, v126
	v_log_f32_e32 v126, v126
	s_nop 0
	v_mul_f32_e32 v133, 0x3f317217, v126
	v_fma_f32 v133, v126, s44, -v133
	v_fmac_f32_e32 v133, 0x3377d1cf, v126
	v_fmac_f32_e32 v133, 0x3f317217, v126
	v_mov_b32_e32 v126, v133
	v_add_f32_e32 v126, v132, v126
	v_max_f32_e32 v132, v127, v127
	v_mul_f32_e64 v127, |v127|, s43
	v_exp_f32_e32 v127, v127
	v_min_f32_e32 v132, 0, v132
	v_add_f32_e32 v127, 1.0, v127
	v_log_f32_e32 v127, v127
	s_nop 0
	v_mul_f32_e32 v133, 0x3f317217, v127
	v_fma_f32 v133, v127, s44, -v133
	v_fmac_f32_e32 v133, 0x3377d1cf, v127
	v_fmac_f32_e32 v133, 0x3f317217, v127
	v_mov_b32_e32 v127, v133
	v_sub_f32_e32 v127, v132, v127
	v_add_f32_e32 v127, v127, v99
	v_max_f32_e32 v132, v143, v127
	v_sub_f32_e32 v127, v98, v127
	v_mul_f32_e64 v127, |v127|, s43
	v_exp_f32_e32 v127, v127
	s_nop 0
	v_add_f32_e32 v127, 1.0, v127
	v_log_f32_e32 v127, v127
	s_nop 0
	v_mul_f32_e32 v133, 0x3f317217, v127
	v_fma_f32 v133, v127, s44, -v133
	v_fmac_f32_e32 v133, 0x3377d1cf, v127
	v_fmac_f32_e32 v133, 0x3f317217, v127
	v_mov_b32_e32 v127, v133
	v_add_f32_e32 v127, v132, v127
	v_max_f32_e32 v132, v120, v120
	v_mul_f32_e64 v120, |v120|, s43
	v_exp_f32_e32 v120, v120
	v_min_f32_e32 v132, 0, v132
	v_add_f32_e32 v120, 1.0, v120
	v_log_f32_e32 v120, v120
	s_nop 0
	v_mul_f32_e32 v133, 0x3f317217, v120
	v_fma_f32 v133, v120, s44, -v133
	v_fmac_f32_e32 v133, 0x3377d1cf, v120
	v_fmac_f32_e32 v133, 0x3f317217, v120
	v_mov_b32_e32 v120, v133
	v_sub_f32_e32 v120, v132, v120
	v_add_f32_e32 v120, v120, v89
	v_max_f32_e32 v132, v159, v120
	v_sub_f32_e32 v120, v88, v120
	v_mul_f32_e64 v120, |v120|, s43
	v_exp_f32_e32 v120, v120
	s_nop 0
	v_add_f32_e32 v120, 1.0, v120
	v_log_f32_e32 v120, v120
	s_nop 0
	v_mul_f32_e32 v133, 0x3f317217, v120
	v_fma_f32 v133, v120, s44, -v133
	v_fmac_f32_e32 v133, 0x3377d1cf, v120
	v_fmac_f32_e32 v133, 0x3f317217, v120
	v_mov_b32_e32 v120, v133
	v_add_f32_e32 v132, v132, v120
	v_max_f32_e32 v120, v121, v121
	v_mul_f32_e64 v121, |v121|, s43
	v_exp_f32_e32 v121, v121
	v_min_f32_e32 v120, 0, v120
	v_add_f32_e32 v121, 1.0, v121
	v_log_f32_e32 v121, v121
	s_nop 0
	v_mul_f32_e32 v133, 0x3f317217, v121
	v_fma_f32 v133, v121, s44, -v133
	v_fmac_f32_e32 v133, 0x3377d1cf, v121
	v_fmac_f32_e32 v133, 0x3f317217, v121
	v_mov_b32_e32 v121, v133
	v_sub_f32_e32 v120, v120, v121
	v_add_f32_e32 v120, v120, v91
	v_max_f32_e32 v121, v167, v120
	v_sub_f32_e32 v120, v90, v120
	v_mul_f32_e64 v120, |v120|, s43
	v_exp_f32_e32 v120, v120
	s_nop 0
	v_add_f32_e32 v120, 1.0, v120
	v_log_f32_e32 v120, v120
	s_nop 0
	v_mul_f32_e32 v133, 0x3f317217, v120
	v_fma_f32 v133, v120, s44, -v133
	v_fmac_f32_e32 v133, 0x3377d1cf, v120
	v_fmac_f32_e32 v133, 0x3f317217, v120
	v_mov_b32_e32 v120, v133
	v_add_f32_e32 v133, v121, v120
	v_mul_f32_e64 v121, |v122|, s43
	v_exp_f32_e32 v121, v121
	v_max_f32_e32 v120, v122, v122
	v_min_f32_e32 v120, 0, v120
	v_add_f32_e32 v121, 1.0, v121
	v_log_f32_e32 v121, v121
	s_nop 0
	v_mul_f32_e32 v122, 0x3f317217, v121
	v_fma_f32 v122, v121, s44, -v122
	v_fmac_f32_e32 v122, 0x3377d1cf, v121
	v_fmac_f32_e32 v122, 0x3f317217, v121
	v_mov_b32_e32 v121, v122
	v_sub_f32_e32 v120, v120, v121
	v_add_f32_e32 v120, v120, v85
	v_max_f32_e32 v121, v168, v120
	v_sub_f32_e32 v120, v84, v120
	v_mul_f32_e64 v120, |v120|, s43
	v_exp_f32_e32 v120, v120
	s_nop 0
	v_add_f32_e32 v120, 1.0, v120
	v_log_f32_e32 v120, v120
	s_nop 0
	v_mul_f32_e32 v122, 0x3f317217, v120
	v_fma_f32 v122, v120, s44, -v122
	v_fmac_f32_e32 v122, 0x3377d1cf, v120
	v_fmac_f32_e32 v122, 0x3f317217, v120
	v_mov_b32_e32 v120, v122
	v_add_f32_e32 v134, v121, v120
	v_mul_f32_e64 v121, |v123|, s43
	v_exp_f32_e32 v121, v121
	v_max_f32_e32 v120, v123, v123
	v_min_f32_e32 v120, 0, v120
	v_add_f32_e32 v121, 1.0, v121
	v_log_f32_e32 v121, v121
	s_nop 0
	v_mul_f32_e32 v122, 0x3f317217, v121
	v_fma_f32 v122, v121, s44, -v122
	v_fmac_f32_e32 v122, 0x3377d1cf, v121
	v_fmac_f32_e32 v122, 0x3f317217, v121
	v_mov_b32_e32 v121, v122
	v_sub_f32_e32 v120, v120, v121
	v_add_f32_e32 v120, v120, v87
	v_max_f32_e32 v121, v169, v120
	v_sub_f32_e32 v120, v86, v120
	v_mul_f32_e64 v120, |v120|, s43
	v_exp_f32_e32 v120, v120
	s_nop 0
	v_add_f32_e32 v120, 1.0, v120
	v_log_f32_e32 v120, v120
	s_nop 0
	v_mul_f32_e32 v122, 0x3f317217, v120
	v_fma_f32 v122, v120, s44, -v122
	v_fmac_f32_e32 v122, 0x3377d1cf, v120
	v_fmac_f32_e32 v122, 0x3f317217, v120
	v_mov_b32_e32 v120, v122
	v_add_f32_e32 v123, v121, v120
	v_cvt_pk_f16_f32 v120, v124, v125
	v_max_f32_e32 v124, v116, v116
	v_mul_f32_e64 v116, |v116|, s43
	v_exp_f32_e32 v116, v116
	v_min_f32_e32 v124, 0, v124
	v_cvt_pk_f16_f32 v121, v126, v127
	v_cvt_pk_f16_f32 v122, v132, v133
	v_add_f32_e32 v116, 1.0, v116
	v_cmp_gt_f32_e32 vcc, s3, v116
	v_cvt_pk_f16_f32 v123, v134, v123
	global_store_dwordx4 v[130:131], v[120:123], off
	v_cndmask_b32_e64 v125, 0, 32, vcc
	v_ldexp_f32 v116, v116, v125
	v_log_f32_e32 v116, v116
	v_or_b32_e32 v120, 48, v158
	v_ashrrev_i32_e32 v121, 31, v120
	v_lshlrev_b64 v[120:121], 11, v[120:121]
	v_mul_f32_e32 v125, 0x3f317217, v116
	v_fma_f32 v125, v116, s44, -v125
	v_fmac_f32_e32 v125, 0x3377d1cf, v116
	v_fmac_f32_e32 v125, 0x3f317217, v116
	v_cmp_lt_f32_e64 s[10:11], |v116|, s45
	v_lshl_add_u64 v[122:123], s[18:19], 0, v[120:121]
	v_lshl_add_u64 v[122:123], v[122:123], 0, v[208:209]
	v_cndmask_b32_e64 v116, v116, v125, s[10:11]
	v_cndmask_b32_e32 v125, 0, v242, vcc
	v_sub_f32_e32 v116, v116, v125
	v_sub_f32_e32 v116, v124, v116
	v_add_f32_e32 v116, v116, v101
	v_max_f32_e32 v124, v140, v116
	v_sub_f32_e32 v116, v100, v116
	v_mul_f32_e64 v116, |v116|, s43
	v_exp_f32_e32 v116, v116
	s_nop 0
	v_add_f32_e32 v116, 1.0, v116
	v_log_f32_e32 v116, v116
	s_nop 0
	v_mul_f32_e32 v125, 0x3f317217, v116
	v_fma_f32 v125, v116, s44, -v125
	v_fmac_f32_e32 v125, 0x3377d1cf, v116
	v_fmac_f32_e32 v125, 0x3f317217, v116
	v_mov_b32_e32 v116, v125
	v_add_f32_e32 v116, v124, v116
	v_max_f32_e32 v124, v117, v117
	v_mul_f32_e64 v117, |v117|, s43
	v_exp_f32_e32 v117, v117
	v_min_f32_e32 v124, 0, v124
	v_add_f32_e32 v117, 1.0, v117
	v_log_f32_e32 v117, v117
	s_nop 0
	v_mul_f32_e32 v125, 0x3f317217, v117
	v_fma_f32 v125, v117, s44, -v125
	v_fmac_f32_e32 v125, 0x3377d1cf, v117
	v_fmac_f32_e32 v125, 0x3f317217, v117
	v_mov_b32_e32 v117, v125
	v_sub_f32_e32 v117, v124, v117
	v_add_f32_e32 v117, v117, v103
	v_max_f32_e32 v124, v141, v117
	v_sub_f32_e32 v117, v102, v117
	v_mul_f32_e64 v117, |v117|, s43
	v_exp_f32_e32 v117, v117
	s_nop 0
	v_add_f32_e32 v117, 1.0, v117
	v_log_f32_e32 v117, v117
	s_nop 0
	v_mul_f32_e32 v125, 0x3f317217, v117
	v_fma_f32 v125, v117, s44, -v125
	v_fmac_f32_e32 v125, 0x3377d1cf, v117
	v_fmac_f32_e32 v125, 0x3f317217, v117
	v_mov_b32_e32 v117, v125
	v_add_f32_e32 v117, v124, v117
	v_max_f32_e32 v124, v118, v118
	v_mul_f32_e64 v118, |v118|, s43
	v_exp_f32_e32 v118, v118
	v_min_f32_e32 v124, 0, v124
	v_add_f32_e32 v118, 1.0, v118
	v_log_f32_e32 v118, v118
	s_nop 0
	v_mul_f32_e32 v125, 0x3f317217, v118
	v_fma_f32 v125, v118, s44, -v125
	v_fmac_f32_e32 v125, 0x3377d1cf, v118
	v_fmac_f32_e32 v125, 0x3f317217, v118
	v_mov_b32_e32 v118, v125
	v_sub_f32_e32 v118, v124, v118
	v_add_f32_e32 v118, v118, v97
	v_max_f32_e32 v124, v142, v118
	v_sub_f32_e32 v118, v96, v118
	v_mul_f32_e64 v118, |v118|, s43
	v_exp_f32_e32 v118, v118
	s_nop 0
	v_add_f32_e32 v118, 1.0, v118
	v_log_f32_e32 v118, v118
	s_nop 0
	v_mul_f32_e32 v125, 0x3f317217, v118
	v_fma_f32 v125, v118, s44, -v125
	v_fmac_f32_e32 v125, 0x3377d1cf, v118
	v_fmac_f32_e32 v125, 0x3f317217, v118
	v_mov_b32_e32 v118, v125
	v_add_f32_e32 v118, v124, v118
	v_max_f32_e32 v124, v119, v119
	v_mul_f32_e64 v119, |v119|, s43
	v_exp_f32_e32 v119, v119
	v_min_f32_e32 v124, 0, v124
	v_add_f32_e32 v119, 1.0, v119
	v_log_f32_e32 v119, v119
	s_nop 0
	v_mul_f32_e32 v125, 0x3f317217, v119
	v_fma_f32 v125, v119, s44, -v125
	v_fmac_f32_e32 v125, 0x3377d1cf, v119
	v_fmac_f32_e32 v125, 0x3f317217, v119
	v_mov_b32_e32 v119, v125
	v_sub_f32_e32 v119, v124, v119
	v_add_f32_e32 v119, v119, v99
	v_max_f32_e32 v124, v143, v119
	v_sub_f32_e32 v119, v98, v119
	v_mul_f32_e64 v119, |v119|, s43
	v_exp_f32_e32 v119, v119
	s_nop 0
	v_add_f32_e32 v119, 1.0, v119
	v_log_f32_e32 v119, v119
	s_nop 0
	v_mul_f32_e32 v125, 0x3f317217, v119
	v_fma_f32 v125, v119, s44, -v125
	v_fmac_f32_e32 v125, 0x3377d1cf, v119
	v_fmac_f32_e32 v125, 0x3f317217, v119
	v_mov_b32_e32 v119, v125
	v_add_f32_e32 v119, v124, v119
	v_max_f32_e32 v124, v112, v112
	v_mul_f32_e64 v112, |v112|, s43
	v_exp_f32_e32 v112, v112
	v_min_f32_e32 v124, 0, v124
	v_add_f32_e32 v112, 1.0, v112
	v_log_f32_e32 v112, v112
	s_nop 0
	v_mul_f32_e32 v125, 0x3f317217, v112
	v_fma_f32 v125, v112, s44, -v125
	v_fmac_f32_e32 v125, 0x3377d1cf, v112
	v_fmac_f32_e32 v125, 0x3f317217, v112
	v_mov_b32_e32 v112, v125
	v_sub_f32_e32 v112, v124, v112
	v_add_f32_e32 v112, v112, v89
	v_max_f32_e32 v124, v159, v112
	v_sub_f32_e32 v112, v88, v112
	v_mul_f32_e64 v112, |v112|, s43
	v_exp_f32_e32 v112, v112
	s_nop 0
	v_add_f32_e32 v112, 1.0, v112
	v_log_f32_e32 v112, v112
	s_nop 0
	v_mul_f32_e32 v125, 0x3f317217, v112
	v_fma_f32 v125, v112, s44, -v125
	v_fmac_f32_e32 v125, 0x3377d1cf, v112
	v_fmac_f32_e32 v125, 0x3f317217, v112
	v_mov_b32_e32 v112, v125
	v_add_f32_e32 v124, v124, v112
	v_max_f32_e32 v112, v113, v113
	v_mul_f32_e64 v113, |v113|, s43
	v_exp_f32_e32 v113, v113
	v_min_f32_e32 v112, 0, v112
	v_add_f32_e32 v113, 1.0, v113
	v_log_f32_e32 v113, v113
	s_nop 0
	v_mul_f32_e32 v125, 0x3f317217, v113
	v_fma_f32 v125, v113, s44, -v125
	v_fmac_f32_e32 v125, 0x3377d1cf, v113
	v_fmac_f32_e32 v125, 0x3f317217, v113
	v_mov_b32_e32 v113, v125
	v_sub_f32_e32 v112, v112, v113
	v_add_f32_e32 v112, v112, v91
	v_max_f32_e32 v113, v167, v112
	v_sub_f32_e32 v112, v90, v112
	v_mul_f32_e64 v112, |v112|, s43
	v_exp_f32_e32 v112, v112
	s_nop 0
	v_add_f32_e32 v112, 1.0, v112
	v_log_f32_e32 v112, v112
	s_nop 0
	v_mul_f32_e32 v125, 0x3f317217, v112
	v_fma_f32 v125, v112, s44, -v125
	v_fmac_f32_e32 v125, 0x3377d1cf, v112
	v_fmac_f32_e32 v125, 0x3f317217, v112
	v_mov_b32_e32 v112, v125
	v_add_f32_e32 v125, v113, v112
	v_mul_f32_e64 v113, |v114|, s43
	v_exp_f32_e32 v113, v113
	v_max_f32_e32 v112, v114, v114
	v_min_f32_e32 v112, 0, v112
	v_add_f32_e32 v113, 1.0, v113
	v_log_f32_e32 v113, v113
	s_nop 0
	v_mul_f32_e32 v114, 0x3f317217, v113
	v_fma_f32 v114, v113, s44, -v114
	v_fmac_f32_e32 v114, 0x3377d1cf, v113
	v_fmac_f32_e32 v114, 0x3f317217, v113
	v_mov_b32_e32 v113, v114
	v_sub_f32_e32 v112, v112, v113
	v_add_f32_e32 v112, v112, v85
	v_max_f32_e32 v113, v168, v112
	v_sub_f32_e32 v112, v84, v112
	v_mul_f32_e64 v112, |v112|, s43
	v_exp_f32_e32 v112, v112
	s_nop 0
	v_add_f32_e32 v112, 1.0, v112
	v_log_f32_e32 v112, v112
	s_nop 0
	v_mul_f32_e32 v114, 0x3f317217, v112
	v_fma_f32 v114, v112, s44, -v114
	v_fmac_f32_e32 v114, 0x3377d1cf, v112
	v_fmac_f32_e32 v114, 0x3f317217, v112
	v_mov_b32_e32 v112, v114
	v_add_f32_e32 v126, v113, v112
	v_mul_f32_e64 v113, |v115|, s43
	v_exp_f32_e32 v113, v113
	v_max_f32_e32 v112, v115, v115
	v_min_f32_e32 v112, 0, v112
	v_add_f32_e32 v113, 1.0, v113
	v_log_f32_e32 v113, v113
	s_nop 0
	v_mul_f32_e32 v114, 0x3f317217, v113
	v_fma_f32 v114, v113, s44, -v114
	v_fmac_f32_e32 v114, 0x3377d1cf, v113
	v_fmac_f32_e32 v114, 0x3f317217, v113
	v_mov_b32_e32 v113, v114
	v_sub_f32_e32 v112, v112, v113
	v_add_f32_e32 v112, v112, v87
	v_max_f32_e32 v113, v169, v112
	v_sub_f32_e32 v112, v86, v112
	v_mul_f32_e64 v112, |v112|, s43
	v_exp_f32_e32 v112, v112
	s_nop 0
	v_add_f32_e32 v112, 1.0, v112
	v_log_f32_e32 v112, v112
	s_nop 0
	v_mul_f32_e32 v114, 0x3f317217, v112
	v_fma_f32 v114, v112, s44, -v114
	v_fmac_f32_e32 v114, 0x3377d1cf, v112
	v_fmac_f32_e32 v114, 0x3f317217, v112
	v_mov_b32_e32 v112, v114
	v_add_f32_e32 v115, v113, v112
	v_cvt_pk_f16_f32 v112, v116, v117
	v_max_f32_e32 v116, v108, v108
	v_mul_f32_e64 v108, |v108|, s43
	v_exp_f32_e32 v108, v108
	v_min_f32_e32 v116, 0, v116
	v_cvt_pk_f16_f32 v113, v118, v119
	v_cvt_pk_f16_f32 v114, v124, v125
	v_add_f32_e32 v108, 1.0, v108
	v_cmp_gt_f32_e32 vcc, s3, v108
	v_cvt_pk_f16_f32 v115, v126, v115
	global_store_dwordx4 v[122:123], v[112:115], off
	v_cndmask_b32_e64 v117, 0, 32, vcc
	v_ldexp_f32 v108, v108, v117
	v_log_f32_e32 v108, v108
	v_lshl_add_u64 v[112:113], v[156:157], 0, s[74:75]
	v_lshl_add_u64 v[114:115], s[18:19], 0, v[112:113]
	v_lshl_add_u64 v[114:115], v[114:115], 0, v[208:209]
	v_mul_f32_e32 v117, 0x3f317217, v108
	v_fma_f32 v117, v108, s44, -v117
	v_fmac_f32_e32 v117, 0x3377d1cf, v108
	v_fmac_f32_e32 v117, 0x3f317217, v108
	v_cmp_lt_f32_e64 s[10:11], |v108|, s45
	s_nop 1
	v_cndmask_b32_e64 v108, v108, v117, s[10:11]
	v_cndmask_b32_e32 v117, 0, v242, vcc
	v_sub_f32_e32 v108, v108, v117
	v_sub_f32_e32 v108, v116, v108
	v_add_f32_e32 v108, v108, v101
	v_max_f32_e32 v116, v140, v108
	v_sub_f32_e32 v108, v100, v108
	v_mul_f32_e64 v108, |v108|, s43
	v_exp_f32_e32 v108, v108
	s_nop 0
	v_add_f32_e32 v108, 1.0, v108
	v_log_f32_e32 v108, v108
	s_nop 0
	v_mul_f32_e32 v117, 0x3f317217, v108
	v_fma_f32 v117, v108, s44, -v117
	v_fmac_f32_e32 v117, 0x3377d1cf, v108
	v_fmac_f32_e32 v117, 0x3f317217, v108
	v_mov_b32_e32 v108, v117
	v_add_f32_e32 v108, v116, v108
	v_max_f32_e32 v116, v109, v109
	v_mul_f32_e64 v109, |v109|, s43
	v_exp_f32_e32 v109, v109
	v_min_f32_e32 v116, 0, v116
	v_add_f32_e32 v109, 1.0, v109
	v_log_f32_e32 v109, v109
	s_nop 0
	v_mul_f32_e32 v117, 0x3f317217, v109
	v_fma_f32 v117, v109, s44, -v117
	v_fmac_f32_e32 v117, 0x3377d1cf, v109
	v_fmac_f32_e32 v117, 0x3f317217, v109
	v_mov_b32_e32 v109, v117
	v_sub_f32_e32 v109, v116, v109
	v_add_f32_e32 v109, v109, v103
	v_max_f32_e32 v116, v141, v109
	v_sub_f32_e32 v109, v102, v109
	v_mul_f32_e64 v109, |v109|, s43
	v_exp_f32_e32 v109, v109
	s_nop 0
	v_add_f32_e32 v109, 1.0, v109
	v_log_f32_e32 v109, v109
	s_nop 0
	v_mul_f32_e32 v117, 0x3f317217, v109
	v_fma_f32 v117, v109, s44, -v117
	v_fmac_f32_e32 v117, 0x3377d1cf, v109
	v_fmac_f32_e32 v117, 0x3f317217, v109
	v_mov_b32_e32 v109, v117
	v_add_f32_e32 v109, v116, v109
	v_max_f32_e32 v116, v110, v110
	v_mul_f32_e64 v110, |v110|, s43
	v_exp_f32_e32 v110, v110
	v_min_f32_e32 v116, 0, v116
	v_add_f32_e32 v110, 1.0, v110
	v_log_f32_e32 v110, v110
	s_nop 0
	v_mul_f32_e32 v117, 0x3f317217, v110
	v_fma_f32 v117, v110, s44, -v117
	v_fmac_f32_e32 v117, 0x3377d1cf, v110
	v_fmac_f32_e32 v117, 0x3f317217, v110
	v_mov_b32_e32 v110, v117
	v_sub_f32_e32 v110, v116, v110
	v_add_f32_e32 v110, v110, v97
	v_max_f32_e32 v116, v142, v110
	v_sub_f32_e32 v110, v96, v110
	v_mul_f32_e64 v110, |v110|, s43
	v_exp_f32_e32 v110, v110
	s_nop 0
	v_add_f32_e32 v110, 1.0, v110
	v_log_f32_e32 v110, v110
	s_nop 0
	v_mul_f32_e32 v117, 0x3f317217, v110
	v_fma_f32 v117, v110, s44, -v117
	v_fmac_f32_e32 v117, 0x3377d1cf, v110
	v_fmac_f32_e32 v117, 0x3f317217, v110
	v_mov_b32_e32 v110, v117
	v_add_f32_e32 v110, v116, v110
	v_max_f32_e32 v116, v111, v111
	v_mul_f32_e64 v111, |v111|, s43
	v_exp_f32_e32 v111, v111
	v_min_f32_e32 v116, 0, v116
	v_add_f32_e32 v111, 1.0, v111
	v_log_f32_e32 v111, v111
	s_nop 0
	v_mul_f32_e32 v117, 0x3f317217, v111
	v_fma_f32 v117, v111, s44, -v117
	v_fmac_f32_e32 v117, 0x3377d1cf, v111
	v_fmac_f32_e32 v117, 0x3f317217, v111
	v_mov_b32_e32 v111, v117
	v_sub_f32_e32 v111, v116, v111
	v_add_f32_e32 v111, v111, v99
	v_max_f32_e32 v116, v143, v111
	v_sub_f32_e32 v111, v98, v111
	v_mul_f32_e64 v111, |v111|, s43
	v_exp_f32_e32 v111, v111
	s_nop 0
	v_add_f32_e32 v111, 1.0, v111
	v_log_f32_e32 v111, v111
	s_nop 0
	v_mul_f32_e32 v117, 0x3f317217, v111
	v_fma_f32 v117, v111, s44, -v117
	v_fmac_f32_e32 v117, 0x3377d1cf, v111
	v_fmac_f32_e32 v117, 0x3f317217, v111
	v_mov_b32_e32 v111, v117
	v_add_f32_e32 v111, v116, v111
	v_max_f32_e32 v116, v104, v104
	v_mul_f32_e64 v104, |v104|, s43
	v_exp_f32_e32 v104, v104
	v_min_f32_e32 v116, 0, v116
	v_add_f32_e32 v104, 1.0, v104
	v_log_f32_e32 v104, v104
	s_nop 0
	v_mul_f32_e32 v117, 0x3f317217, v104
	v_fma_f32 v117, v104, s44, -v117
	v_fmac_f32_e32 v117, 0x3377d1cf, v104
	v_fmac_f32_e32 v117, 0x3f317217, v104
	v_mov_b32_e32 v104, v117
	v_sub_f32_e32 v104, v116, v104
	v_add_f32_e32 v104, v104, v89
	v_max_f32_e32 v116, v159, v104
	v_sub_f32_e32 v104, v88, v104
	v_mul_f32_e64 v104, |v104|, s43
	v_exp_f32_e32 v104, v104
	s_nop 0
	v_add_f32_e32 v104, 1.0, v104
	v_log_f32_e32 v104, v104
	s_nop 0
	v_mul_f32_e32 v117, 0x3f317217, v104
	v_fma_f32 v117, v104, s44, -v117
	v_fmac_f32_e32 v117, 0x3377d1cf, v104
	v_fmac_f32_e32 v117, 0x3f317217, v104
	v_mov_b32_e32 v104, v117
	v_add_f32_e32 v116, v116, v104
	v_max_f32_e32 v104, v105, v105
	v_mul_f32_e64 v105, |v105|, s43
	v_exp_f32_e32 v105, v105
	v_min_f32_e32 v104, 0, v104
	v_add_f32_e32 v105, 1.0, v105
	v_log_f32_e32 v105, v105
	s_nop 0
	v_mul_f32_e32 v117, 0x3f317217, v105
	v_fma_f32 v117, v105, s44, -v117
	v_fmac_f32_e32 v117, 0x3377d1cf, v105
	v_fmac_f32_e32 v117, 0x3f317217, v105
	v_mov_b32_e32 v105, v117
	v_sub_f32_e32 v104, v104, v105
	v_add_f32_e32 v104, v104, v91
	v_max_f32_e32 v105, v167, v104
	v_sub_f32_e32 v104, v90, v104
	v_mul_f32_e64 v104, |v104|, s43
	v_exp_f32_e32 v104, v104
	s_nop 0
	v_add_f32_e32 v104, 1.0, v104
	v_log_f32_e32 v104, v104
	s_nop 0
	v_mul_f32_e32 v117, 0x3f317217, v104
	v_fma_f32 v117, v104, s44, -v117
	v_fmac_f32_e32 v117, 0x3377d1cf, v104
	v_fmac_f32_e32 v117, 0x3f317217, v104
	v_mov_b32_e32 v104, v117
	v_add_f32_e32 v117, v105, v104
	v_mul_f32_e64 v105, |v106|, s43
	v_exp_f32_e32 v105, v105
	v_max_f32_e32 v104, v106, v106
	v_min_f32_e32 v104, 0, v104
	v_add_f32_e32 v105, 1.0, v105
	v_log_f32_e32 v105, v105
	s_nop 0
	v_mul_f32_e32 v106, 0x3f317217, v105
	v_fma_f32 v106, v105, s44, -v106
	v_fmac_f32_e32 v106, 0x3377d1cf, v105
	v_fmac_f32_e32 v106, 0x3f317217, v105
	v_mov_b32_e32 v105, v106
	v_sub_f32_e32 v104, v104, v105
	v_add_f32_e32 v104, v104, v85
	v_max_f32_e32 v105, v168, v104
	v_sub_f32_e32 v104, v84, v104
	v_mul_f32_e64 v104, |v104|, s43
	v_exp_f32_e32 v104, v104
	s_nop 0
	v_add_f32_e32 v104, 1.0, v104
	v_log_f32_e32 v104, v104
	s_nop 0
	v_mul_f32_e32 v106, 0x3f317217, v104
	v_fma_f32 v106, v104, s44, -v106
	v_fmac_f32_e32 v106, 0x3377d1cf, v104
	v_fmac_f32_e32 v106, 0x3f317217, v104
	v_mov_b32_e32 v104, v106
	v_add_f32_e32 v118, v105, v104
	v_mul_f32_e64 v105, |v107|, s43
	v_exp_f32_e32 v105, v105
	v_max_f32_e32 v104, v107, v107
	v_min_f32_e32 v104, 0, v104
	v_add_f32_e32 v105, 1.0, v105
	v_log_f32_e32 v105, v105
	s_nop 0
	v_mul_f32_e32 v106, 0x3f317217, v105
	v_fma_f32 v106, v105, s44, -v106
	v_fmac_f32_e32 v106, 0x3377d1cf, v105
	v_fmac_f32_e32 v106, 0x3f317217, v105
	v_mov_b32_e32 v105, v106
	v_sub_f32_e32 v104, v104, v105
	v_add_f32_e32 v104, v104, v87
	v_max_f32_e32 v105, v169, v104
	v_sub_f32_e32 v104, v86, v104
	v_mul_f32_e64 v104, |v104|, s43
	v_exp_f32_e32 v104, v104
	s_nop 0
	v_add_f32_e32 v104, 1.0, v104
	v_log_f32_e32 v104, v104
	s_nop 0
	v_mul_f32_e32 v106, 0x3f317217, v104
	v_fma_f32 v106, v104, s44, -v106
	v_fmac_f32_e32 v106, 0x3377d1cf, v104
	v_fmac_f32_e32 v106, 0x3f317217, v104
	v_mov_b32_e32 v104, v106
	v_add_f32_e32 v107, v105, v104
	v_cvt_pk_f16_f32 v104, v108, v109
	v_max_f32_e32 v108, v92, v92
	v_mul_f32_e64 v92, |v92|, s43
	v_exp_f32_e32 v92, v92
	v_min_f32_e32 v108, 0, v108
	v_cvt_pk_f16_f32 v105, v110, v111
	v_cvt_pk_f16_f32 v106, v116, v117
	v_add_f32_e32 v92, 1.0, v92
	v_cmp_gt_f32_e32 vcc, s3, v92
	v_cvt_pk_f16_f32 v107, v118, v107
	global_store_dwordx4 v[114:115], v[104:107], off
	v_cndmask_b32_e64 v109, 0, 32, vcc
	v_ldexp_f32 v92, v92, v109
	v_log_f32_e32 v92, v92
	v_lshl_add_u64 v[104:105], v[156:157], 0, s[4:5]
	v_lshl_add_u64 v[106:107], s[18:19], 0, v[104:105]
	v_lshl_add_u64 v[106:107], v[106:107], 0, v[208:209]
	v_mul_f32_e32 v109, 0x3f317217, v92
	v_fma_f32 v109, v92, s44, -v109
	v_fmac_f32_e32 v109, 0x3377d1cf, v92
	v_fmac_f32_e32 v109, 0x3f317217, v92
	v_cmp_lt_f32_e64 s[10:11], |v92|, s45
	s_nop 1
	v_cndmask_b32_e64 v92, v92, v109, s[10:11]
	v_cndmask_b32_e32 v109, 0, v242, vcc
	v_sub_f32_e32 v92, v92, v109
	v_sub_f32_e32 v92, v108, v92
	v_add_f32_e32 v92, v92, v101
	v_max_f32_e32 v108, v140, v92
	v_sub_f32_e32 v92, v100, v92
	v_mul_f32_e64 v92, |v92|, s43
	v_exp_f32_e32 v92, v92
	s_nop 0
	v_add_f32_e32 v92, 1.0, v92
	v_log_f32_e32 v92, v92
	s_nop 0
	v_mul_f32_e32 v109, 0x3f317217, v92
	v_fma_f32 v109, v92, s44, -v109
	v_fmac_f32_e32 v109, 0x3377d1cf, v92
	v_fmac_f32_e32 v109, 0x3f317217, v92
	v_mov_b32_e32 v92, v109
	v_add_f32_e32 v92, v108, v92
	v_max_f32_e32 v108, v93, v93
	v_mul_f32_e64 v93, |v93|, s43
	v_exp_f32_e32 v93, v93
	v_min_f32_e32 v108, 0, v108
	v_add_f32_e32 v93, 1.0, v93
	v_log_f32_e32 v93, v93
	s_nop 0
	v_mul_f32_e32 v109, 0x3f317217, v93
	v_fma_f32 v109, v93, s44, -v109
	v_fmac_f32_e32 v109, 0x3377d1cf, v93
	v_fmac_f32_e32 v109, 0x3f317217, v93
	v_mov_b32_e32 v93, v109
	v_sub_f32_e32 v93, v108, v93
	v_add_f32_e32 v93, v93, v103
	v_max_f32_e32 v108, v141, v93
	v_sub_f32_e32 v93, v102, v93
	v_mul_f32_e64 v93, |v93|, s43
	v_exp_f32_e32 v93, v93
	s_nop 0
	v_add_f32_e32 v93, 1.0, v93
	v_log_f32_e32 v93, v93
	s_nop 0
	v_mul_f32_e32 v109, 0x3f317217, v93
	v_fma_f32 v109, v93, s44, -v109
	v_fmac_f32_e32 v109, 0x3377d1cf, v93
	v_fmac_f32_e32 v109, 0x3f317217, v93
	v_mov_b32_e32 v93, v109
	v_add_f32_e32 v93, v108, v93
	v_max_f32_e32 v108, v94, v94
	v_mul_f32_e64 v94, |v94|, s43
	v_exp_f32_e32 v94, v94
	v_min_f32_e32 v108, 0, v108
	v_add_f32_e32 v94, 1.0, v94
	v_log_f32_e32 v94, v94
	s_nop 0
	v_mul_f32_e32 v109, 0x3f317217, v94
	v_fma_f32 v109, v94, s44, -v109
	v_fmac_f32_e32 v109, 0x3377d1cf, v94
	v_fmac_f32_e32 v109, 0x3f317217, v94
	v_mov_b32_e32 v94, v109
	v_sub_f32_e32 v94, v108, v94
	v_add_f32_e32 v94, v94, v97
	v_max_f32_e32 v108, v142, v94
	v_sub_f32_e32 v94, v96, v94
	v_mul_f32_e64 v94, |v94|, s43
	v_exp_f32_e32 v94, v94
	s_nop 0
	v_add_f32_e32 v94, 1.0, v94
	v_log_f32_e32 v94, v94
	s_nop 0
	v_mul_f32_e32 v109, 0x3f317217, v94
	v_fma_f32 v109, v94, s44, -v109
	v_fmac_f32_e32 v109, 0x3377d1cf, v94
	v_fmac_f32_e32 v109, 0x3f317217, v94
	v_mov_b32_e32 v94, v109
	v_add_f32_e32 v94, v108, v94
	v_max_f32_e32 v108, v95, v95
	v_mul_f32_e64 v95, |v95|, s43
	v_exp_f32_e32 v95, v95
	v_min_f32_e32 v108, 0, v108
	v_add_f32_e32 v95, 1.0, v95
	v_log_f32_e32 v95, v95
	s_nop 0
	v_mul_f32_e32 v109, 0x3f317217, v95
	v_fma_f32 v109, v95, s44, -v109
	v_fmac_f32_e32 v109, 0x3377d1cf, v95
	v_fmac_f32_e32 v109, 0x3f317217, v95
	v_mov_b32_e32 v95, v109
	v_sub_f32_e32 v95, v108, v95
	v_add_f32_e32 v95, v95, v99
	v_max_f32_e32 v108, v143, v95
	v_sub_f32_e32 v95, v98, v95
	v_mul_f32_e64 v95, |v95|, s43
	v_exp_f32_e32 v95, v95
	s_nop 0
	v_add_f32_e32 v95, 1.0, v95
	v_log_f32_e32 v95, v95
	s_nop 0
	v_mul_f32_e32 v109, 0x3f317217, v95
	v_fma_f32 v109, v95, s44, -v109
	v_fmac_f32_e32 v109, 0x3377d1cf, v95
	v_fmac_f32_e32 v109, 0x3f317217, v95
	v_mov_b32_e32 v95, v109
	v_add_f32_e32 v95, v108, v95
	v_max_f32_e32 v108, v80, v80
	v_mul_f32_e64 v80, |v80|, s43
	v_exp_f32_e32 v80, v80
	v_min_f32_e32 v108, 0, v108
	v_add_f32_e32 v80, 1.0, v80
	v_log_f32_e32 v80, v80
	s_nop 0
	v_mul_f32_e32 v109, 0x3f317217, v80
	v_fma_f32 v109, v80, s44, -v109
	v_fmac_f32_e32 v109, 0x3377d1cf, v80
	v_fmac_f32_e32 v109, 0x3f317217, v80
	v_mov_b32_e32 v80, v109
	v_sub_f32_e32 v80, v108, v80
	v_add_f32_e32 v80, v80, v89
	v_max_f32_e32 v108, v159, v80
	v_sub_f32_e32 v80, v88, v80
	v_mul_f32_e64 v80, |v80|, s43
	v_exp_f32_e32 v80, v80
	s_nop 0
	v_add_f32_e32 v80, 1.0, v80
	v_log_f32_e32 v80, v80
	s_nop 0
	v_mul_f32_e32 v109, 0x3f317217, v80
	v_fma_f32 v109, v80, s44, -v109
	v_fmac_f32_e32 v109, 0x3377d1cf, v80
	v_fmac_f32_e32 v109, 0x3f317217, v80
	v_mov_b32_e32 v80, v109
	v_add_f32_e32 v108, v108, v80
	v_max_f32_e32 v80, v81, v81
	v_mul_f32_e64 v81, |v81|, s43
	v_exp_f32_e32 v81, v81
	v_min_f32_e32 v80, 0, v80
	v_add_f32_e32 v81, 1.0, v81
	v_log_f32_e32 v81, v81
	s_nop 0
	v_mul_f32_e32 v109, 0x3f317217, v81
	v_fma_f32 v109, v81, s44, -v109
	v_fmac_f32_e32 v109, 0x3377d1cf, v81
	v_fmac_f32_e32 v109, 0x3f317217, v81
	v_mov_b32_e32 v81, v109
	v_sub_f32_e32 v80, v80, v81
	v_add_f32_e32 v80, v80, v91
	v_max_f32_e32 v81, v167, v80
	v_sub_f32_e32 v80, v90, v80
	v_mul_f32_e64 v80, |v80|, s43
	v_exp_f32_e32 v80, v80
	s_nop 0
	v_add_f32_e32 v80, 1.0, v80
	v_log_f32_e32 v80, v80
	s_nop 0
	v_mul_f32_e32 v109, 0x3f317217, v80
	v_fma_f32 v109, v80, s44, -v109
	v_fmac_f32_e32 v109, 0x3377d1cf, v80
	v_fmac_f32_e32 v109, 0x3f317217, v80
	v_mov_b32_e32 v80, v109
	v_add_f32_e32 v109, v81, v80
	v_mul_f32_e64 v81, |v82|, s43
	v_exp_f32_e32 v81, v81
	v_max_f32_e32 v80, v82, v82
	v_min_f32_e32 v80, 0, v80
	v_add_f32_e32 v81, 1.0, v81
	v_log_f32_e32 v81, v81
	s_nop 0
	v_mul_f32_e32 v82, 0x3f317217, v81
	v_fma_f32 v82, v81, s44, -v82
	v_fmac_f32_e32 v82, 0x3377d1cf, v81
	v_fmac_f32_e32 v82, 0x3f317217, v81
	v_mov_b32_e32 v81, v82
	v_sub_f32_e32 v80, v80, v81
	v_add_f32_e32 v80, v80, v85
	v_max_f32_e32 v81, v168, v80
	v_sub_f32_e32 v80, v84, v80
	v_mul_f32_e64 v80, |v80|, s43
	v_exp_f32_e32 v80, v80
	s_nop 0
	v_add_f32_e32 v80, 1.0, v80
	v_log_f32_e32 v80, v80
	s_nop 0
	v_mul_f32_e32 v82, 0x3f317217, v80
	v_fma_f32 v82, v80, s44, -v82
	v_fmac_f32_e32 v82, 0x3377d1cf, v80
	v_fmac_f32_e32 v82, 0x3f317217, v80
	v_mov_b32_e32 v80, v82
	v_add_f32_e32 v110, v81, v80
	v_mul_f32_e64 v81, |v83|, s43
	v_exp_f32_e32 v81, v81
	v_max_f32_e32 v80, v83, v83
	v_min_f32_e32 v80, 0, v80
	v_add_f32_e32 v81, 1.0, v81
	v_log_f32_e32 v81, v81
	s_nop 0
	v_mul_f32_e32 v82, 0x3f317217, v81
	v_fma_f32 v82, v81, s44, -v82
	v_fmac_f32_e32 v82, 0x3377d1cf, v81
	v_fmac_f32_e32 v82, 0x3f317217, v81
	v_mov_b32_e32 v81, v82
	v_sub_f32_e32 v80, v80, v81
	v_add_f32_e32 v80, v80, v87
	v_max_f32_e32 v81, v169, v80
	v_sub_f32_e32 v80, v86, v80
	v_mul_f32_e64 v80, |v80|, s43
	v_exp_f32_e32 v80, v80
	s_nop 0
	v_add_f32_e32 v80, 1.0, v80
	v_log_f32_e32 v80, v80
	s_nop 0
	v_mul_f32_e32 v82, 0x3f317217, v80
	v_fma_f32 v82, v80, s44, -v82
	v_fmac_f32_e32 v82, 0x3377d1cf, v80
	v_fmac_f32_e32 v82, 0x3f317217, v80
	v_mov_b32_e32 v80, v82
	v_add_f32_e32 v83, v81, v80
	v_cvt_pk_f16_f32 v80, v92, v93
	v_max_f32_e32 v92, v76, v76
	v_mul_f32_e64 v76, |v76|, s43
	v_exp_f32_e32 v76, v76
	v_min_f32_e32 v92, 0, v92
	v_cvt_pk_f16_f32 v81, v94, v95
	v_cvt_pk_f16_f32 v82, v108, v109
	v_add_f32_e32 v76, 1.0, v76
	v_cmp_gt_f32_e32 vcc, s3, v76
	v_cvt_pk_f16_f32 v83, v110, v83
	global_store_dwordx4 v[106:107], v[80:83], off
	v_cndmask_b32_e64 v93, 0, 32, vcc
	v_ldexp_f32 v76, v76, v93
	v_log_f32_e32 v76, v76
	v_lshl_add_u64 v[82:83], v[156:157], 0, s[82:83]
	v_lshl_add_u64 v[80:81], s[18:19], 0, v[82:83]
	v_lshl_add_u64 v[80:81], v[80:81], 0, v[208:209]
	v_mul_f32_e32 v93, 0x3f317217, v76
	v_fma_f32 v93, v76, s44, -v93
	v_fmac_f32_e32 v93, 0x3377d1cf, v76
	v_fmac_f32_e32 v93, 0x3f317217, v76
	v_cmp_lt_f32_e64 s[10:11], |v76|, s45
	s_nop 1
	v_cndmask_b32_e64 v76, v76, v93, s[10:11]
	v_cndmask_b32_e32 v93, 0, v242, vcc
	v_sub_f32_e32 v76, v76, v93
	v_sub_f32_e32 v76, v92, v76
	v_add_f32_e32 v76, v76, v101
	v_max_f32_e32 v92, v140, v76
	v_sub_f32_e32 v76, v100, v76
	v_mul_f32_e64 v76, |v76|, s43
	v_exp_f32_e32 v76, v76
	s_nop 0
	v_add_f32_e32 v76, 1.0, v76
	v_log_f32_e32 v76, v76
	s_nop 0
	v_mul_f32_e32 v93, 0x3f317217, v76
	v_fma_f32 v93, v76, s44, -v93
	v_fmac_f32_e32 v93, 0x3377d1cf, v76
	v_fmac_f32_e32 v93, 0x3f317217, v76
	v_mov_b32_e32 v76, v93
	v_add_f32_e32 v76, v92, v76
	v_max_f32_e32 v92, v77, v77
	v_mul_f32_e64 v77, |v77|, s43
	v_exp_f32_e32 v77, v77
	v_min_f32_e32 v92, 0, v92
	v_add_f32_e32 v77, 1.0, v77
	v_log_f32_e32 v77, v77
	s_nop 0
	v_mul_f32_e32 v93, 0x3f317217, v77
	v_fma_f32 v93, v77, s44, -v93
	v_fmac_f32_e32 v93, 0x3377d1cf, v77
	v_fmac_f32_e32 v93, 0x3f317217, v77
	v_mov_b32_e32 v77, v93
	v_sub_f32_e32 v77, v92, v77
	v_add_f32_e32 v77, v77, v103
	v_max_f32_e32 v92, v141, v77
	v_sub_f32_e32 v77, v102, v77
	v_mul_f32_e64 v77, |v77|, s43
	v_exp_f32_e32 v77, v77
	s_nop 0
	v_add_f32_e32 v77, 1.0, v77
	v_log_f32_e32 v77, v77
	s_nop 0
	v_mul_f32_e32 v93, 0x3f317217, v77
	v_fma_f32 v93, v77, s44, -v93
	v_fmac_f32_e32 v93, 0x3377d1cf, v77
	v_fmac_f32_e32 v93, 0x3f317217, v77
	v_mov_b32_e32 v77, v93
	v_add_f32_e32 v77, v92, v77
	v_max_f32_e32 v92, v78, v78
	v_mul_f32_e64 v78, |v78|, s43
	v_exp_f32_e32 v78, v78
	v_min_f32_e32 v92, 0, v92
	v_add_f32_e32 v78, 1.0, v78
	v_log_f32_e32 v78, v78
	s_nop 0
	v_mul_f32_e32 v93, 0x3f317217, v78
	v_fma_f32 v93, v78, s44, -v93
	v_fmac_f32_e32 v93, 0x3377d1cf, v78
	v_fmac_f32_e32 v93, 0x3f317217, v78
	v_mov_b32_e32 v78, v93
	v_sub_f32_e32 v78, v92, v78
	v_add_f32_e32 v78, v78, v97
	v_max_f32_e32 v92, v142, v78
	v_sub_f32_e32 v78, v96, v78
	v_mul_f32_e64 v78, |v78|, s43
	v_exp_f32_e32 v78, v78
	s_nop 0
	v_add_f32_e32 v78, 1.0, v78
	v_log_f32_e32 v78, v78
	s_nop 0
	v_mul_f32_e32 v93, 0x3f317217, v78
	v_fma_f32 v93, v78, s44, -v93
	v_fmac_f32_e32 v93, 0x3377d1cf, v78
	v_fmac_f32_e32 v93, 0x3f317217, v78
	v_mov_b32_e32 v78, v93
	v_add_f32_e32 v78, v92, v78
	v_max_f32_e32 v92, v79, v79
	v_mul_f32_e64 v79, |v79|, s43
	v_exp_f32_e32 v79, v79
	v_min_f32_e32 v92, 0, v92
	v_add_f32_e32 v79, 1.0, v79
	v_log_f32_e32 v79, v79
	s_nop 0
	v_mul_f32_e32 v93, 0x3f317217, v79
	v_fma_f32 v93, v79, s44, -v93
	v_fmac_f32_e32 v93, 0x3377d1cf, v79
	v_fmac_f32_e32 v93, 0x3f317217, v79
	v_mov_b32_e32 v79, v93
	v_sub_f32_e32 v79, v92, v79
	v_add_f32_e32 v79, v79, v99
	v_max_f32_e32 v92, v143, v79
	v_sub_f32_e32 v79, v98, v79
	v_mul_f32_e64 v79, |v79|, s43
	v_exp_f32_e32 v79, v79
	s_nop 0
	v_add_f32_e32 v79, 1.0, v79
	v_log_f32_e32 v79, v79
	s_nop 0
	v_mul_f32_e32 v93, 0x3f317217, v79
	v_fma_f32 v93, v79, s44, -v93
	v_fmac_f32_e32 v93, 0x3377d1cf, v79
	v_fmac_f32_e32 v93, 0x3f317217, v79
	v_mov_b32_e32 v79, v93
	v_add_f32_e32 v79, v92, v79
	v_max_f32_e32 v92, v72, v72
	v_mul_f32_e64 v72, |v72|, s43
	v_exp_f32_e32 v72, v72
	v_min_f32_e32 v92, 0, v92
	v_add_f32_e32 v72, 1.0, v72
	v_log_f32_e32 v72, v72
	s_nop 0
	v_mul_f32_e32 v93, 0x3f317217, v72
	v_fma_f32 v93, v72, s44, -v93
	v_fmac_f32_e32 v93, 0x3377d1cf, v72
	v_fmac_f32_e32 v93, 0x3f317217, v72
	v_mov_b32_e32 v72, v93
	v_sub_f32_e32 v72, v92, v72
	v_add_f32_e32 v72, v72, v89
	v_max_f32_e32 v92, v159, v72
	v_sub_f32_e32 v72, v88, v72
	v_mul_f32_e64 v72, |v72|, s43
	v_exp_f32_e32 v72, v72
	s_nop 0
	v_add_f32_e32 v72, 1.0, v72
	v_log_f32_e32 v72, v72
	s_nop 0
	v_mul_f32_e32 v93, 0x3f317217, v72
	v_fma_f32 v93, v72, s44, -v93
	v_fmac_f32_e32 v93, 0x3377d1cf, v72
	v_fmac_f32_e32 v93, 0x3f317217, v72
	v_mov_b32_e32 v72, v93
	v_add_f32_e32 v92, v92, v72
	v_max_f32_e32 v72, v73, v73
	v_mul_f32_e64 v73, |v73|, s43
	v_exp_f32_e32 v73, v73
	v_min_f32_e32 v72, 0, v72
	v_add_f32_e32 v73, 1.0, v73
	v_log_f32_e32 v73, v73
	s_nop 0
	v_mul_f32_e32 v93, 0x3f317217, v73
	v_fma_f32 v93, v73, s44, -v93
	v_fmac_f32_e32 v93, 0x3377d1cf, v73
	v_fmac_f32_e32 v93, 0x3f317217, v73
	v_mov_b32_e32 v73, v93
	v_sub_f32_e32 v72, v72, v73
	v_add_f32_e32 v72, v72, v91
	v_max_f32_e32 v73, v167, v72
	v_sub_f32_e32 v72, v90, v72
	v_mul_f32_e64 v72, |v72|, s43
	v_exp_f32_e32 v72, v72
	s_nop 0
	v_add_f32_e32 v72, 1.0, v72
	v_log_f32_e32 v72, v72
	s_nop 0
	v_mul_f32_e32 v93, 0x3f317217, v72
	v_fma_f32 v93, v72, s44, -v93
	v_fmac_f32_e32 v93, 0x3377d1cf, v72
	v_fmac_f32_e32 v93, 0x3f317217, v72
	v_mov_b32_e32 v72, v93
	v_add_f32_e32 v93, v73, v72
	v_mul_f32_e64 v73, |v74|, s43
	v_exp_f32_e32 v73, v73
	v_max_f32_e32 v72, v74, v74
	v_min_f32_e32 v72, 0, v72
	v_add_f32_e32 v73, 1.0, v73
	v_log_f32_e32 v73, v73
	s_nop 0
	v_mul_f32_e32 v74, 0x3f317217, v73
	v_fma_f32 v74, v73, s44, -v74
	v_fmac_f32_e32 v74, 0x3377d1cf, v73
	v_fmac_f32_e32 v74, 0x3f317217, v73
	v_mov_b32_e32 v73, v74
	v_sub_f32_e32 v72, v72, v73
	v_add_f32_e32 v72, v72, v85
	v_max_f32_e32 v73, v168, v72
	v_sub_f32_e32 v72, v84, v72
	v_mul_f32_e64 v72, |v72|, s43
	v_exp_f32_e32 v72, v72
	s_nop 0
	v_add_f32_e32 v72, 1.0, v72
	v_log_f32_e32 v72, v72
	s_nop 0
	v_mul_f32_e32 v74, 0x3f317217, v72
	v_fma_f32 v74, v72, s44, -v74
	v_fmac_f32_e32 v74, 0x3377d1cf, v72
	v_fmac_f32_e32 v74, 0x3f317217, v72
	v_mov_b32_e32 v72, v74
	v_add_f32_e32 v94, v73, v72
	v_mul_f32_e64 v73, |v75|, s43
	v_exp_f32_e32 v73, v73
	v_max_f32_e32 v72, v75, v75
	v_min_f32_e32 v72, 0, v72
	v_add_f32_e32 v73, 1.0, v73
	v_log_f32_e32 v73, v73
	s_nop 0
	v_mul_f32_e32 v74, 0x3f317217, v73
	v_fma_f32 v74, v73, s44, -v74
	v_fmac_f32_e32 v74, 0x3377d1cf, v73
	v_fmac_f32_e32 v74, 0x3f317217, v73
	v_mov_b32_e32 v73, v74
	v_sub_f32_e32 v72, v72, v73
	v_add_f32_e32 v72, v72, v87
	v_max_f32_e32 v73, v169, v72
	v_sub_f32_e32 v72, v86, v72
	v_mul_f32_e64 v72, |v72|, s43
	v_exp_f32_e32 v72, v72
	s_nop 0
	v_add_f32_e32 v72, 1.0, v72
	v_log_f32_e32 v72, v72
	s_nop 0
	v_mul_f32_e32 v74, 0x3f317217, v72
	v_fma_f32 v74, v72, s44, -v74
	v_fmac_f32_e32 v74, 0x3377d1cf, v72
	v_fmac_f32_e32 v74, 0x3f317217, v72
	v_mov_b32_e32 v72, v74
	v_add_f32_e32 v75, v73, v72
	v_cvt_pk_f16_f32 v72, v76, v77
	v_cvt_pk_f16_f32 v73, v78, v79
	v_cvt_pk_f16_f32 v74, v92, v93
	v_cvt_pk_f16_f32 v75, v94, v75
	global_store_dwordx4 v[80:81], v[72:75], off
	v_lshl_add_u64 v[80:81], v[156:157], 0, s[84:85]
	s_nop 0
	v_max_f32_e32 v74, v68, v68
	v_mul_f32_e64 v68, |v68|, s43
	v_exp_f32_e32 v68, v68
	v_min_f32_e32 v74, 0, v74
	v_lshl_add_u64 v[72:73], s[18:19], 0, v[80:81]
	v_lshl_add_u64 v[72:73], v[72:73], 0, v[208:209]
	v_add_f32_e32 v68, 1.0, v68
	v_log_f32_e32 v68, v68
	s_nop 0
	v_mul_f32_e32 v75, 0x3f317217, v68
	v_fma_f32 v75, v68, s44, -v75
	v_fmac_f32_e32 v75, 0x3377d1cf, v68
	v_fmac_f32_e32 v75, 0x3f317217, v68
	v_mov_b32_e32 v68, v75
	v_sub_f32_e32 v68, v74, v68
	v_add_f32_e32 v68, v68, v101
	v_max_f32_e32 v74, v140, v68
	v_sub_f32_e32 v68, v100, v68
	v_mul_f32_e64 v68, |v68|, s43
	v_exp_f32_e32 v68, v68
	s_nop 0
	v_add_f32_e32 v68, 1.0, v68
	v_log_f32_e32 v68, v68
	s_nop 0
	v_mul_f32_e32 v75, 0x3f317217, v68
	v_fma_f32 v75, v68, s44, -v75
	v_fmac_f32_e32 v75, 0x3377d1cf, v68
	v_fmac_f32_e32 v75, 0x3f317217, v68
	v_mov_b32_e32 v68, v75
	v_add_f32_e32 v68, v74, v68
	v_max_f32_e32 v74, v69, v69
	v_mul_f32_e64 v69, |v69|, s43
	v_exp_f32_e32 v69, v69
	v_min_f32_e32 v74, 0, v74
	v_add_f32_e32 v69, 1.0, v69
	v_log_f32_e32 v69, v69
	s_nop 0
	v_mul_f32_e32 v75, 0x3f317217, v69
	v_fma_f32 v75, v69, s44, -v75
	v_fmac_f32_e32 v75, 0x3377d1cf, v69
	v_fmac_f32_e32 v75, 0x3f317217, v69
	v_mov_b32_e32 v69, v75
	v_sub_f32_e32 v69, v74, v69
	v_add_f32_e32 v69, v69, v103
	v_max_f32_e32 v74, v141, v69
	v_sub_f32_e32 v69, v102, v69
	v_mul_f32_e64 v69, |v69|, s43
	v_exp_f32_e32 v69, v69
	s_nop 0
	v_add_f32_e32 v69, 1.0, v69
	v_log_f32_e32 v69, v69
	s_nop 0
	v_mul_f32_e32 v75, 0x3f317217, v69
	v_fma_f32 v75, v69, s44, -v75
	v_fmac_f32_e32 v75, 0x3377d1cf, v69
	v_fmac_f32_e32 v75, 0x3f317217, v69
	v_mov_b32_e32 v69, v75
	v_add_f32_e32 v69, v74, v69
	v_max_f32_e32 v74, v70, v70
	v_mul_f32_e64 v70, |v70|, s43
	v_exp_f32_e32 v70, v70
	v_min_f32_e32 v74, 0, v74
	v_add_f32_e32 v70, 1.0, v70
	v_log_f32_e32 v70, v70
	s_nop 0
	v_mul_f32_e32 v75, 0x3f317217, v70
	v_fma_f32 v75, v70, s44, -v75
	v_fmac_f32_e32 v75, 0x3377d1cf, v70
	v_fmac_f32_e32 v75, 0x3f317217, v70
	v_mov_b32_e32 v70, v75
	v_sub_f32_e32 v70, v74, v70
	v_add_f32_e32 v70, v70, v97
	v_max_f32_e32 v74, v142, v70
	v_sub_f32_e32 v70, v96, v70
	v_mul_f32_e64 v70, |v70|, s43
	v_exp_f32_e32 v70, v70
	s_nop 0
	v_add_f32_e32 v70, 1.0, v70
	v_log_f32_e32 v70, v70
	s_nop 0
	v_mul_f32_e32 v75, 0x3f317217, v70
	v_fma_f32 v75, v70, s44, -v75
	v_fmac_f32_e32 v75, 0x3377d1cf, v70
	v_fmac_f32_e32 v75, 0x3f317217, v70
	v_mov_b32_e32 v70, v75
	v_add_f32_e32 v70, v74, v70
	v_max_f32_e32 v74, v71, v71
	v_mul_f32_e64 v71, |v71|, s43
	v_exp_f32_e32 v71, v71
	v_min_f32_e32 v74, 0, v74
	v_add_f32_e32 v71, 1.0, v71
	v_log_f32_e32 v71, v71
	s_nop 0
	v_mul_f32_e32 v75, 0x3f317217, v71
	v_fma_f32 v75, v71, s44, -v75
	v_fmac_f32_e32 v75, 0x3377d1cf, v71
	v_fmac_f32_e32 v75, 0x3f317217, v71
	v_mov_b32_e32 v71, v75
	v_sub_f32_e32 v71, v74, v71
	v_add_f32_e32 v71, v71, v99
	v_max_f32_e32 v74, v143, v71
	v_sub_f32_e32 v71, v98, v71
	v_mul_f32_e64 v71, |v71|, s43
	v_exp_f32_e32 v71, v71
	s_nop 0
	v_add_f32_e32 v71, 1.0, v71
	v_log_f32_e32 v71, v71
	s_nop 0
	v_mul_f32_e32 v75, 0x3f317217, v71
	v_fma_f32 v75, v71, s44, -v75
	v_fmac_f32_e32 v75, 0x3377d1cf, v71
	v_fmac_f32_e32 v75, 0x3f317217, v71
	v_mov_b32_e32 v71, v75
	v_add_f32_e32 v71, v74, v71
	v_max_f32_e32 v74, v64, v64
	v_mul_f32_e64 v64, |v64|, s43
	v_exp_f32_e32 v64, v64
	v_min_f32_e32 v74, 0, v74
	v_add_f32_e32 v64, 1.0, v64
	v_log_f32_e32 v64, v64
	s_nop 0
	v_mul_f32_e32 v75, 0x3f317217, v64
	v_fma_f32 v75, v64, s44, -v75
	v_fmac_f32_e32 v75, 0x3377d1cf, v64
	v_fmac_f32_e32 v75, 0x3f317217, v64
	v_mov_b32_e32 v64, v75
	v_sub_f32_e32 v64, v74, v64
	v_add_f32_e32 v64, v64, v89
	v_max_f32_e32 v74, v159, v64
	v_sub_f32_e32 v64, v88, v64
	v_mul_f32_e64 v64, |v64|, s43
	v_exp_f32_e32 v64, v64
	s_nop 0
	v_add_f32_e32 v64, 1.0, v64
	v_log_f32_e32 v64, v64
	s_nop 0
	v_mul_f32_e32 v75, 0x3f317217, v64
	v_fma_f32 v75, v64, s44, -v75
	v_fmac_f32_e32 v75, 0x3377d1cf, v64
	v_fmac_f32_e32 v75, 0x3f317217, v64
	v_mov_b32_e32 v64, v75
	v_add_f32_e32 v74, v74, v64
	v_max_f32_e32 v64, v65, v65
	v_mul_f32_e64 v65, |v65|, s43
	v_exp_f32_e32 v65, v65
	v_min_f32_e32 v64, 0, v64
	v_add_f32_e32 v65, 1.0, v65
	v_log_f32_e32 v65, v65
	s_nop 0
	v_mul_f32_e32 v75, 0x3f317217, v65
	v_fma_f32 v75, v65, s44, -v75
	v_fmac_f32_e32 v75, 0x3377d1cf, v65
	v_fmac_f32_e32 v75, 0x3f317217, v65
	v_mov_b32_e32 v65, v75
	v_sub_f32_e32 v64, v64, v65
	v_add_f32_e32 v64, v64, v91
	v_max_f32_e32 v65, v167, v64
	v_sub_f32_e32 v64, v90, v64
	v_mul_f32_e64 v64, |v64|, s43
	v_exp_f32_e32 v64, v64
	s_nop 0
	v_add_f32_e32 v64, 1.0, v64
	v_log_f32_e32 v64, v64
	s_nop 0
	v_mul_f32_e32 v75, 0x3f317217, v64
	v_fma_f32 v75, v64, s44, -v75
	v_fmac_f32_e32 v75, 0x3377d1cf, v64
	v_fmac_f32_e32 v75, 0x3f317217, v64
	v_mov_b32_e32 v64, v75
	v_add_f32_e32 v75, v65, v64
	v_mul_f32_e64 v65, |v66|, s43
	v_exp_f32_e32 v65, v65
	v_max_f32_e32 v64, v66, v66
	v_min_f32_e32 v64, 0, v64
	v_add_f32_e32 v65, 1.0, v65
	v_log_f32_e32 v65, v65
	s_nop 0
	v_mul_f32_e32 v66, 0x3f317217, v65
	v_fma_f32 v66, v65, s44, -v66
	v_fmac_f32_e32 v66, 0x3377d1cf, v65
	v_fmac_f32_e32 v66, 0x3f317217, v65
	v_mov_b32_e32 v65, v66
	v_sub_f32_e32 v64, v64, v65
	v_add_f32_e32 v64, v64, v85
	v_max_f32_e32 v65, v168, v64
	v_sub_f32_e32 v64, v84, v64
	v_mul_f32_e64 v64, |v64|, s43
	v_exp_f32_e32 v64, v64
	v_lshl_add_u64 v[84:85], s[90:91], 0, v[156:157]
	v_lshl_add_u64 v[84:85], v[84:85], 0, v[208:209]
	v_add_f32_e32 v64, 1.0, v64
	v_log_f32_e32 v64, v64
	s_nop 0
	v_mul_f32_e32 v66, 0x3f317217, v64
	v_fma_f32 v66, v64, s44, -v66
	v_fmac_f32_e32 v66, 0x3377d1cf, v64
	v_fmac_f32_e32 v66, 0x3f317217, v64
	v_mov_b32_e32 v64, v66
	v_add_f32_e32 v76, v65, v64
	v_mul_f32_e64 v65, |v67|, s43
	v_exp_f32_e32 v65, v65
	v_max_f32_e32 v64, v67, v67
	v_min_f32_e32 v64, 0, v64
	v_add_f32_e32 v65, 1.0, v65
	v_log_f32_e32 v65, v65
	s_nop 0
	v_mul_f32_e32 v66, 0x3f317217, v65
	v_fma_f32 v66, v65, s44, -v66
	v_fmac_f32_e32 v66, 0x3377d1cf, v65
	v_fmac_f32_e32 v66, 0x3f317217, v65
	v_mov_b32_e32 v65, v66
	v_sub_f32_e32 v64, v64, v65
	v_add_f32_e32 v64, v64, v87
	v_max_f32_e32 v65, v169, v64
	v_sub_f32_e32 v64, v86, v64
	v_mul_f32_e64 v64, |v64|, s43
	v_exp_f32_e32 v64, v64
	v_max_f32_e32 v86, v60, v60
	v_mul_f32_e64 v60, |v60|, s43
	v_exp_f32_e32 v60, v60
	v_add_f32_e32 v64, 1.0, v64
	v_cmp_gt_f32_e32 vcc, s3, v64
	v_min_f32_e32 v86, 0, v86
	v_add_f32_e32 v60, 1.0, v60
	v_cndmask_b32_e64 v66, 0, 32, vcc
	v_ldexp_f32 v64, v64, v66
	v_log_f32_e32 v64, v64
	s_nop 0
	v_mul_f32_e32 v66, 0x3f317217, v64
	v_fma_f32 v66, v64, s44, -v66
	v_fmac_f32_e32 v66, 0x3377d1cf, v64
	v_fmac_f32_e32 v66, 0x3f317217, v64
	v_cmp_lt_f32_e64 s[10:11], |v64|, s45
	s_nop 1
	v_cndmask_b32_e64 v64, v64, v66, s[10:11]
	v_cndmask_b32_e32 v66, 0, v242, vcc
	v_sub_f32_e32 v64, v64, v66
	v_add_f32_e32 v67, v65, v64
	v_cvt_pk_f16_f32 v64, v68, v69
	v_cvt_pk_f16_f32 v65, v70, v71
	v_cvt_pk_f16_f32 v66, v74, v75
	v_cvt_pk_f16_f32 v67, v76, v67
	global_store_dwordx4 v[72:73], v[64:67], off
	global_load_dwordx4 v[64:67], v166, s[14:15] offset:1072
	s_nop 0
	global_load_dwordx4 v[68:71], v166, s[14:15] offset:1056
	global_load_dwordx4 v[72:75], v166, s[14:15] offset:1040
	global_load_dwordx4 v[76:79], v166, s[14:15] offset:1024
	v_log_f32_e32 v60, v60
	s_nop 0
	v_mul_f32_e32 v87, 0x3f317217, v60
	v_fma_f32 v87, v60, s44, -v87
	v_fmac_f32_e32 v87, 0x3377d1cf, v60
	v_fmac_f32_e32 v87, 0x3f317217, v60
	v_mov_b32_e32 v60, v87
	v_sub_f32_e32 v60, v86, v60
	s_waitcnt vmcnt(0)
	v_add_f32_e32 v86, v60, v77
	v_max_f32_e32 v60, v76, v76
	v_max_f32_e32 v87, v60, v86
	v_sub_f32_e32 v86, v76, v86
	v_mul_f32_e64 v86, |v86|, s43
	v_exp_f32_e32 v86, v86
	s_nop 0
	v_add_f32_e32 v86, 1.0, v86
	v_log_f32_e32 v86, v86
	s_nop 0
	v_mul_f32_e32 v88, 0x3f317217, v86
	v_fma_f32 v88, v86, s44, -v88
	v_fmac_f32_e32 v88, 0x3377d1cf, v86
	v_fmac_f32_e32 v88, 0x3f317217, v86
	v_mov_b32_e32 v86, v88
	v_add_f32_e32 v88, v87, v86
	v_max_f32_e32 v86, v61, v61
	v_mul_f32_e64 v61, |v61|, s43
	v_exp_f32_e32 v61, v61
	v_min_f32_e32 v86, 0, v86
	v_add_f32_e32 v61, 1.0, v61
	v_log_f32_e32 v61, v61
	s_nop 0
	v_mul_f32_e32 v87, 0x3f317217, v61
	v_fma_f32 v87, v61, s44, -v87
	v_fmac_f32_e32 v87, 0x3377d1cf, v61
	v_fmac_f32_e32 v87, 0x3f317217, v61
	v_mov_b32_e32 v61, v87
	v_sub_f32_e32 v61, v86, v61
	v_add_f32_e32 v86, v61, v79
	v_max_f32_e32 v61, v78, v78
	v_max_f32_e32 v87, v61, v86
	v_sub_f32_e32 v86, v78, v86
	v_mul_f32_e64 v86, |v86|, s43
	v_exp_f32_e32 v86, v86
	s_nop 0
	v_add_f32_e32 v86, 1.0, v86
	v_log_f32_e32 v86, v86
	s_nop 0
	v_mul_f32_e32 v89, 0x3f317217, v86
	v_fma_f32 v89, v86, s44, -v89
	v_fmac_f32_e32 v89, 0x3377d1cf, v86
	v_fmac_f32_e32 v89, 0x3f317217, v86
	v_mov_b32_e32 v86, v89
	v_add_f32_e32 v89, v87, v86
	v_max_f32_e32 v86, v62, v62
	v_mul_f32_e64 v62, |v62|, s43
	v_exp_f32_e32 v62, v62
	v_min_f32_e32 v86, 0, v86
	v_cvt_pk_f16_f32 v88, v88, v89
	v_add_f32_e32 v62, 1.0, v62
	v_log_f32_e32 v62, v62
	s_nop 0
	v_mul_f32_e32 v87, 0x3f317217, v62
	v_fma_f32 v87, v62, s44, -v87
	v_fmac_f32_e32 v87, 0x3377d1cf, v62
	v_fmac_f32_e32 v87, 0x3f317217, v62
	v_mov_b32_e32 v62, v87
	v_sub_f32_e32 v62, v86, v62
	v_add_f32_e32 v86, v62, v73
	v_max_f32_e32 v62, v72, v72
	v_max_f32_e32 v87, v62, v86
	v_sub_f32_e32 v86, v72, v86
	v_mul_f32_e64 v86, |v86|, s43
	v_exp_f32_e32 v86, v86
	s_nop 0
	v_add_f32_e32 v86, 1.0, v86
	v_log_f32_e32 v86, v86
	s_nop 0
	v_mul_f32_e32 v90, 0x3f317217, v86
	v_fma_f32 v90, v86, s44, -v90
	v_fmac_f32_e32 v90, 0x3377d1cf, v86
	v_fmac_f32_e32 v90, 0x3f317217, v86
	v_mov_b32_e32 v86, v90
	v_add_f32_e32 v90, v87, v86
	v_max_f32_e32 v86, v63, v63
	v_mul_f32_e64 v63, |v63|, s43
	v_exp_f32_e32 v63, v63
	v_min_f32_e32 v86, 0, v86
	v_add_f32_e32 v63, 1.0, v63
	v_log_f32_e32 v63, v63
	s_nop 0
	v_mul_f32_e32 v87, 0x3f317217, v63
	v_fma_f32 v87, v63, s44, -v87
	v_fmac_f32_e32 v87, 0x3377d1cf, v63
	v_fmac_f32_e32 v87, 0x3f317217, v63
	v_mov_b32_e32 v63, v87
	v_sub_f32_e32 v63, v86, v63
	v_add_f32_e32 v86, v63, v75
	v_max_f32_e32 v63, v74, v74
	v_max_f32_e32 v87, v63, v86
	v_sub_f32_e32 v86, v74, v86
	v_mul_f32_e64 v86, |v86|, s43
	v_exp_f32_e32 v86, v86
	s_nop 0
	v_add_f32_e32 v86, 1.0, v86
	v_log_f32_e32 v86, v86
	s_nop 0
	v_mul_f32_e32 v91, 0x3f317217, v86
	v_fma_f32 v91, v86, s44, -v91
	v_fmac_f32_e32 v91, 0x3377d1cf, v86
	v_fmac_f32_e32 v91, 0x3f317217, v86
	v_mov_b32_e32 v86, v91
	v_add_f32_e32 v91, v87, v86
	v_max_f32_e32 v86, v56, v56
	v_mul_f32_e64 v56, |v56|, s43
	v_exp_f32_e32 v56, v56
	v_min_f32_e32 v86, 0, v86
	v_cvt_pk_f16_f32 v89, v90, v91
	v_add_f32_e32 v56, 1.0, v56
	v_log_f32_e32 v56, v56
	s_nop 0
	v_mul_f32_e32 v87, 0x3f317217, v56
	v_fma_f32 v87, v56, s44, -v87
	v_fmac_f32_e32 v87, 0x3377d1cf, v56
	v_fmac_f32_e32 v87, 0x3f317217, v56
	v_mov_b32_e32 v56, v87
	v_sub_f32_e32 v56, v86, v56
	v_add_f32_e32 v56, v56, v69
	v_max_f32_e32 v86, v68, v68
	v_max_f32_e32 v87, v86, v56
	v_sub_f32_e32 v56, v68, v56
	v_mul_f32_e64 v56, |v56|, s43
	v_exp_f32_e32 v56, v56
	s_nop 0
	v_add_f32_e32 v56, 1.0, v56
	v_log_f32_e32 v56, v56
	s_nop 0
	v_mul_f32_e32 v92, 0x3f317217, v56
	v_fma_f32 v92, v56, s44, -v92
	v_fmac_f32_e32 v92, 0x3377d1cf, v56
	v_fmac_f32_e32 v92, 0x3f317217, v56
	v_mov_b32_e32 v56, v92
	v_add_f32_e32 v56, v87, v56
	v_max_f32_e32 v87, v57, v57
	v_mul_f32_e64 v57, |v57|, s43
	v_exp_f32_e32 v57, v57
	v_min_f32_e32 v87, 0, v87
	v_add_f32_e32 v57, 1.0, v57
	v_log_f32_e32 v57, v57
	s_nop 0
	v_mul_f32_e32 v92, 0x3f317217, v57
	v_fma_f32 v92, v57, s44, -v92
	v_fmac_f32_e32 v92, 0x3377d1cf, v57
	v_fmac_f32_e32 v92, 0x3f317217, v57
	v_mov_b32_e32 v57, v92
	v_sub_f32_e32 v57, v87, v57
	v_add_f32_e32 v57, v57, v71
	v_max_f32_e32 v87, v70, v70
	v_max_f32_e32 v92, v87, v57
	v_sub_f32_e32 v57, v70, v57
	v_mul_f32_e64 v57, |v57|, s43
	v_exp_f32_e32 v57, v57
	s_nop 0
	v_add_f32_e32 v57, 1.0, v57
	v_log_f32_e32 v57, v57
	s_nop 0
	v_mul_f32_e32 v93, 0x3f317217, v57
	v_fma_f32 v93, v57, s44, -v93
	v_fmac_f32_e32 v93, 0x3377d1cf, v57
	v_fmac_f32_e32 v93, 0x3f317217, v57
	v_mov_b32_e32 v57, v93
	v_add_f32_e32 v57, v92, v57
	v_max_f32_e32 v92, v58, v58
	v_mul_f32_e64 v58, |v58|, s43
	v_exp_f32_e32 v58, v58
	v_min_f32_e32 v92, 0, v92
	v_cvt_pk_f16_f32 v90, v56, v57
	v_add_f32_e32 v58, 1.0, v58
	v_log_f32_e32 v58, v58
	s_nop 0
	v_mul_f32_e32 v93, 0x3f317217, v58
	v_fma_f32 v93, v58, s44, -v93
	v_fmac_f32_e32 v93, 0x3377d1cf, v58
	v_fmac_f32_e32 v93, 0x3f317217, v58
	v_mov_b32_e32 v58, v93
	v_sub_f32_e32 v58, v92, v58
	v_add_f32_e32 v92, v58, v65
	v_max_f32_e32 v58, v64, v64
	v_max_f32_e32 v93, v58, v92
	v_sub_f32_e32 v92, v64, v92
	v_mul_f32_e64 v92, |v92|, s43
	v_exp_f32_e32 v92, v92
	s_nop 0
	v_add_f32_e32 v92, 1.0, v92
	v_log_f32_e32 v92, v92
	s_nop 0
	v_mul_f32_e32 v94, 0x3f317217, v92
	v_fma_f32 v94, v92, s44, -v94
	v_fmac_f32_e32 v94, 0x3377d1cf, v92
	v_fmac_f32_e32 v94, 0x3f317217, v92
	v_mov_b32_e32 v92, v94
	v_add_f32_e32 v92, v93, v92
	v_max_f32_e32 v93, v59, v59
	v_mul_f32_e64 v59, |v59|, s43
	v_exp_f32_e32 v59, v59
	v_min_f32_e32 v93, 0, v93
	v_add_f32_e32 v59, 1.0, v59
	v_log_f32_e32 v59, v59
	s_nop 0
	v_mul_f32_e32 v94, 0x3f317217, v59
	v_fma_f32 v94, v59, s44, -v94
	v_fmac_f32_e32 v94, 0x3377d1cf, v59
	v_fmac_f32_e32 v94, 0x3f317217, v59
	v_mov_b32_e32 v59, v94
	v_sub_f32_e32 v59, v93, v59
	v_add_f32_e32 v93, v59, v67
	v_max_f32_e32 v59, v66, v66
	v_max_f32_e32 v94, v59, v93
	v_sub_f32_e32 v93, v66, v93
	v_mul_f32_e64 v93, |v93|, s43
	v_exp_f32_e32 v93, v93
	s_nop 0
	v_add_f32_e32 v93, 1.0, v93
	v_cmp_gt_f32_e32 vcc, s3, v93
	s_nop 1
	v_cndmask_b32_e64 v95, 0, 32, vcc
	v_ldexp_f32 v93, v93, v95
	v_log_f32_e32 v93, v93
	s_nop 0
	v_mul_f32_e32 v95, 0x3f317217, v93
	v_fma_f32 v95, v93, s44, -v95
	v_fmac_f32_e32 v95, 0x3377d1cf, v93
	v_fmac_f32_e32 v95, 0x3f317217, v93
	v_cmp_lt_f32_e64 s[10:11], |v93|, s45
	s_nop 1
	v_cndmask_b32_e64 v93, v93, v95, s[10:11]
	v_cndmask_b32_e32 v95, 0, v242, vcc
	v_add_co_u32_e32 v56, vcc, s20, v84
	v_max_f32_e32 v84, v52, v52
	v_mul_f32_e64 v52, |v52|, s43
	v_exp_f32_e32 v52, v52
	v_addc_co_u32_e32 v57, vcc, 0, v85, vcc
	v_min_f32_e32 v84, 0, v84
	v_add_f32_e32 v52, 1.0, v52
	v_cmp_gt_f32_e32 vcc, s3, v52
	v_sub_f32_e32 v93, v93, v95
	v_add_f32_e32 v93, v94, v93
	v_cndmask_b32_e64 v85, 0, 32, vcc
	v_ldexp_f32 v52, v52, v85
	v_log_f32_e32 v52, v52
	v_cvt_pk_f16_f32 v91, v92, v93
	global_store_dwordx4 v[56:57], v[88:91], off offset:256
	v_lshl_add_u64 v[56:57], s[90:91], 0, v[136:137]
	v_mul_f32_e32 v85, 0x3f317217, v52
	v_fma_f32 v85, v52, s44, -v85
	v_fmac_f32_e32 v85, 0x3377d1cf, v52
	v_fmac_f32_e32 v85, 0x3f317217, v52
	v_cmp_lt_f32_e64 s[10:11], |v52|, s45
	v_lshl_add_u64 v[56:57], v[56:57], 0, v[208:209]
	s_nop 0
	v_cndmask_b32_e64 v52, v52, v85, s[10:11]
	v_cndmask_b32_e32 v85, 0, v242, vcc
	v_sub_f32_e32 v52, v52, v85
	v_sub_f32_e32 v52, v84, v52
	v_add_f32_e32 v52, v52, v77
	v_max_f32_e32 v84, v60, v52
	v_sub_f32_e32 v52, v76, v52
	v_mul_f32_e64 v52, |v52|, s43
	v_exp_f32_e32 v52, v52
	s_nop 0
	v_add_f32_e32 v52, 1.0, v52
	v_log_f32_e32 v52, v52
	s_nop 0
	v_mul_f32_e32 v85, 0x3f317217, v52
	v_fma_f32 v85, v52, s44, -v85
	v_fmac_f32_e32 v85, 0x3377d1cf, v52
	v_fmac_f32_e32 v85, 0x3f317217, v52
	v_mov_b32_e32 v52, v85
	v_add_f32_e32 v52, v84, v52
	v_max_f32_e32 v84, v53, v53
	v_mul_f32_e64 v53, |v53|, s43
	v_exp_f32_e32 v53, v53
	v_min_f32_e32 v84, 0, v84
	v_add_f32_e32 v53, 1.0, v53
	v_log_f32_e32 v53, v53
	s_nop 0
	v_mul_f32_e32 v85, 0x3f317217, v53
	v_fma_f32 v85, v53, s44, -v85
	v_fmac_f32_e32 v85, 0x3377d1cf, v53
	v_fmac_f32_e32 v85, 0x3f317217, v53
	v_mov_b32_e32 v53, v85
	v_sub_f32_e32 v53, v84, v53
	v_add_f32_e32 v53, v53, v79
	v_max_f32_e32 v84, v61, v53
	v_sub_f32_e32 v53, v78, v53
	v_mul_f32_e64 v53, |v53|, s43
	v_exp_f32_e32 v53, v53
	s_nop 0
	v_add_f32_e32 v53, 1.0, v53
	v_log_f32_e32 v53, v53
	s_nop 0
	v_mul_f32_e32 v85, 0x3f317217, v53
	v_fma_f32 v85, v53, s44, -v85
	v_fmac_f32_e32 v85, 0x3377d1cf, v53
	v_fmac_f32_e32 v85, 0x3f317217, v53
	v_mov_b32_e32 v53, v85
	v_add_f32_e32 v53, v84, v53
	v_max_f32_e32 v84, v54, v54
	v_mul_f32_e64 v54, |v54|, s43
	v_exp_f32_e32 v54, v54
	v_min_f32_e32 v84, 0, v84
	v_add_f32_e32 v54, 1.0, v54
	v_log_f32_e32 v54, v54
	s_nop 0
	v_mul_f32_e32 v85, 0x3f317217, v54
	v_fma_f32 v85, v54, s44, -v85
	v_fmac_f32_e32 v85, 0x3377d1cf, v54
	v_fmac_f32_e32 v85, 0x3f317217, v54
	v_mov_b32_e32 v54, v85
	v_sub_f32_e32 v54, v84, v54
	v_add_f32_e32 v54, v54, v73
	v_max_f32_e32 v84, v62, v54
	v_sub_f32_e32 v54, v72, v54
	v_mul_f32_e64 v54, |v54|, s43
	v_exp_f32_e32 v54, v54
	s_nop 0
	v_add_f32_e32 v54, 1.0, v54
	v_log_f32_e32 v54, v54
	s_nop 0
	v_mul_f32_e32 v85, 0x3f317217, v54
	v_fma_f32 v85, v54, s44, -v85
	v_fmac_f32_e32 v85, 0x3377d1cf, v54
	v_fmac_f32_e32 v85, 0x3f317217, v54
	v_mov_b32_e32 v54, v85
	v_add_f32_e32 v54, v84, v54
	v_max_f32_e32 v84, v55, v55
	v_mul_f32_e64 v55, |v55|, s43
	v_exp_f32_e32 v55, v55
	v_min_f32_e32 v84, 0, v84
	v_add_f32_e32 v55, 1.0, v55
	v_log_f32_e32 v55, v55
	s_nop 0
	v_mul_f32_e32 v85, 0x3f317217, v55
	v_fma_f32 v85, v55, s44, -v85
	v_fmac_f32_e32 v85, 0x3377d1cf, v55
	v_fmac_f32_e32 v85, 0x3f317217, v55
	v_mov_b32_e32 v55, v85
	v_sub_f32_e32 v55, v84, v55
	v_add_f32_e32 v55, v55, v75
	v_max_f32_e32 v84, v63, v55
	v_sub_f32_e32 v55, v74, v55
	v_mul_f32_e64 v55, |v55|, s43
	v_exp_f32_e32 v55, v55
	s_nop 0
	v_add_f32_e32 v55, 1.0, v55
	v_log_f32_e32 v55, v55
	s_nop 0
	v_mul_f32_e32 v85, 0x3f317217, v55
	v_fma_f32 v85, v55, s44, -v85
	v_fmac_f32_e32 v85, 0x3377d1cf, v55
	v_fmac_f32_e32 v85, 0x3f317217, v55
	v_mov_b32_e32 v55, v85
	v_add_f32_e32 v55, v84, v55
	v_max_f32_e32 v84, v48, v48
	v_mul_f32_e64 v48, |v48|, s43
	v_exp_f32_e32 v48, v48
	v_min_f32_e32 v84, 0, v84
	v_add_f32_e32 v48, 1.0, v48
	v_log_f32_e32 v48, v48
	s_nop 0
	v_mul_f32_e32 v85, 0x3f317217, v48
	v_fma_f32 v85, v48, s44, -v85
	v_fmac_f32_e32 v85, 0x3377d1cf, v48
	v_fmac_f32_e32 v85, 0x3f317217, v48
	v_mov_b32_e32 v48, v85
	v_sub_f32_e32 v48, v84, v48
	v_add_f32_e32 v48, v48, v69
	v_max_f32_e32 v84, v86, v48
	v_sub_f32_e32 v48, v68, v48
	v_mul_f32_e64 v48, |v48|, s43
	v_exp_f32_e32 v48, v48
	s_nop 0
	v_add_f32_e32 v48, 1.0, v48
	v_log_f32_e32 v48, v48
	s_nop 0
	v_mul_f32_e32 v85, 0x3f317217, v48
	v_fma_f32 v85, v48, s44, -v85
	v_fmac_f32_e32 v85, 0x3377d1cf, v48
	v_fmac_f32_e32 v85, 0x3f317217, v48
	v_mov_b32_e32 v48, v85
	v_add_f32_e32 v84, v84, v48
	v_max_f32_e32 v48, v49, v49
	v_mul_f32_e64 v49, |v49|, s43
	v_exp_f32_e32 v49, v49
	v_min_f32_e32 v48, 0, v48
	v_add_f32_e32 v49, 1.0, v49
	v_log_f32_e32 v49, v49
	s_nop 0
	v_mul_f32_e32 v85, 0x3f317217, v49
	v_fma_f32 v85, v49, s44, -v85
	v_fmac_f32_e32 v85, 0x3377d1cf, v49
	v_fmac_f32_e32 v85, 0x3f317217, v49
	v_mov_b32_e32 v49, v85
	v_sub_f32_e32 v48, v48, v49
	v_add_f32_e32 v48, v48, v71
	v_max_f32_e32 v49, v87, v48
	v_sub_f32_e32 v48, v70, v48
	v_mul_f32_e64 v48, |v48|, s43
	v_exp_f32_e32 v48, v48
	s_nop 0
	v_add_f32_e32 v48, 1.0, v48
	v_log_f32_e32 v48, v48
	s_nop 0
	v_mul_f32_e32 v85, 0x3f317217, v48
	v_fma_f32 v85, v48, s44, -v85
	v_fmac_f32_e32 v85, 0x3377d1cf, v48
	v_fmac_f32_e32 v85, 0x3f317217, v48
	v_mov_b32_e32 v48, v85
	v_add_f32_e32 v85, v49, v48
	v_mul_f32_e64 v49, |v50|, s43
	v_exp_f32_e32 v49, v49
	v_max_f32_e32 v48, v50, v50
	v_min_f32_e32 v48, 0, v48
	v_add_f32_e32 v49, 1.0, v49
	v_log_f32_e32 v49, v49
	s_nop 0
	v_mul_f32_e32 v50, 0x3f317217, v49
	v_fma_f32 v50, v49, s44, -v50
	v_fmac_f32_e32 v50, 0x3377d1cf, v49
	v_fmac_f32_e32 v50, 0x3f317217, v49
	v_mov_b32_e32 v49, v50
	v_sub_f32_e32 v48, v48, v49
	v_add_f32_e32 v48, v48, v65
	v_max_f32_e32 v49, v58, v48
	v_sub_f32_e32 v48, v64, v48
	v_mul_f32_e64 v48, |v48|, s43
	v_exp_f32_e32 v48, v48
	s_nop 0
	v_add_f32_e32 v48, 1.0, v48
	v_log_f32_e32 v48, v48
	s_nop 0
	v_mul_f32_e32 v50, 0x3f317217, v48
	v_fma_f32 v50, v48, s44, -v50
	v_fmac_f32_e32 v50, 0x3377d1cf, v48
	v_fmac_f32_e32 v50, 0x3f317217, v48
	v_mov_b32_e32 v48, v50
	v_add_f32_e32 v88, v49, v48
	v_mul_f32_e64 v49, |v51|, s43
	v_exp_f32_e32 v49, v49
	v_max_f32_e32 v48, v51, v51
	v_min_f32_e32 v48, 0, v48
	v_add_f32_e32 v49, 1.0, v49
	v_log_f32_e32 v49, v49
	s_nop 0
	v_mul_f32_e32 v50, 0x3f317217, v49
	v_fma_f32 v50, v49, s44, -v50
	v_fmac_f32_e32 v50, 0x3377d1cf, v49
	v_fmac_f32_e32 v50, 0x3f317217, v49
	v_mov_b32_e32 v49, v50
	v_sub_f32_e32 v48, v48, v49
	v_add_f32_e32 v48, v48, v67
	v_max_f32_e32 v49, v59, v48
	v_sub_f32_e32 v48, v66, v48
	v_mul_f32_e64 v48, |v48|, s43
	v_exp_f32_e32 v48, v48
	s_nop 0
	v_add_f32_e32 v48, 1.0, v48
	v_log_f32_e32 v48, v48
	s_nop 0
	v_mul_f32_e32 v50, 0x3f317217, v48
	v_fma_f32 v50, v48, s44, -v50
	v_fmac_f32_e32 v50, 0x3377d1cf, v48
	v_fmac_f32_e32 v50, 0x3f317217, v48
	v_mov_b32_e32 v48, v50
	v_add_f32_e32 v51, v49, v48
	v_cvt_pk_f16_f32 v48, v52, v53
	v_add_co_u32_e32 v52, vcc, s20, v56
	v_cvt_pk_f16_f32 v49, v54, v55
	v_cvt_pk_f16_f32 v50, v84, v85
	v_cvt_pk_f16_f32 v51, v88, v51
	v_addc_co_u32_e32 v53, vcc, 0, v57, vcc
	global_store_dwordx4 v[52:53], v[48:51], off offset:256
	s_nop 1
	v_max_f32_e32 v50, v44, v44
	v_mul_f32_e64 v44, |v44|, s43
	v_exp_f32_e32 v44, v44
	v_min_f32_e32 v50, 0, v50
	v_lshl_add_u64 v[48:49], s[90:91], 0, v[128:129]
	v_lshl_add_u64 v[48:49], v[48:49], 0, v[208:209]
	v_add_f32_e32 v44, 1.0, v44
	v_log_f32_e32 v44, v44
	s_nop 0
	v_mul_f32_e32 v51, 0x3f317217, v44
	v_fma_f32 v51, v44, s44, -v51
	v_fmac_f32_e32 v51, 0x3377d1cf, v44
	v_fmac_f32_e32 v51, 0x3f317217, v44
	v_mov_b32_e32 v44, v51
	v_sub_f32_e32 v44, v50, v44
	v_add_f32_e32 v44, v44, v77
	v_max_f32_e32 v50, v60, v44
	v_sub_f32_e32 v44, v76, v44
	v_mul_f32_e64 v44, |v44|, s43
	v_exp_f32_e32 v44, v44
	s_nop 0
	v_add_f32_e32 v44, 1.0, v44
	v_log_f32_e32 v44, v44
	s_nop 0
	v_mul_f32_e32 v51, 0x3f317217, v44
	v_fma_f32 v51, v44, s44, -v51
	v_fmac_f32_e32 v51, 0x3377d1cf, v44
	v_fmac_f32_e32 v51, 0x3f317217, v44
	v_mov_b32_e32 v44, v51
	v_add_f32_e32 v44, v50, v44
	v_max_f32_e32 v50, v45, v45
	v_mul_f32_e64 v45, |v45|, s43
	v_exp_f32_e32 v45, v45
	v_min_f32_e32 v50, 0, v50
	v_add_f32_e32 v45, 1.0, v45
	v_log_f32_e32 v45, v45
	s_nop 0
	v_mul_f32_e32 v51, 0x3f317217, v45
	v_fma_f32 v51, v45, s44, -v51
	v_fmac_f32_e32 v51, 0x3377d1cf, v45
	v_fmac_f32_e32 v51, 0x3f317217, v45
	v_mov_b32_e32 v45, v51
	v_sub_f32_e32 v45, v50, v45
	v_add_f32_e32 v45, v45, v79
	v_max_f32_e32 v50, v61, v45
	v_sub_f32_e32 v45, v78, v45
	v_mul_f32_e64 v45, |v45|, s43
	v_exp_f32_e32 v45, v45
	s_nop 0
	v_add_f32_e32 v45, 1.0, v45
	v_log_f32_e32 v45, v45
	s_nop 0
	v_mul_f32_e32 v51, 0x3f317217, v45
	v_fma_f32 v51, v45, s44, -v51
	v_fmac_f32_e32 v51, 0x3377d1cf, v45
	v_fmac_f32_e32 v51, 0x3f317217, v45
	v_mov_b32_e32 v45, v51
	v_add_f32_e32 v45, v50, v45
	v_max_f32_e32 v50, v46, v46
	v_mul_f32_e64 v46, |v46|, s43
	v_exp_f32_e32 v46, v46
	v_min_f32_e32 v50, 0, v50
	v_add_f32_e32 v46, 1.0, v46
	v_log_f32_e32 v46, v46
	s_nop 0
	v_mul_f32_e32 v51, 0x3f317217, v46
	v_fma_f32 v51, v46, s44, -v51
	v_fmac_f32_e32 v51, 0x3377d1cf, v46
	v_fmac_f32_e32 v51, 0x3f317217, v46
	v_mov_b32_e32 v46, v51
	v_sub_f32_e32 v46, v50, v46
	v_add_f32_e32 v46, v46, v73
	v_max_f32_e32 v50, v62, v46
	v_sub_f32_e32 v46, v72, v46
	v_mul_f32_e64 v46, |v46|, s43
	v_exp_f32_e32 v46, v46
	s_nop 0
	v_add_f32_e32 v46, 1.0, v46
	v_log_f32_e32 v46, v46
	s_nop 0
	v_mul_f32_e32 v51, 0x3f317217, v46
	v_fma_f32 v51, v46, s44, -v51
	v_fmac_f32_e32 v51, 0x3377d1cf, v46
	v_fmac_f32_e32 v51, 0x3f317217, v46
	v_mov_b32_e32 v46, v51
	v_add_f32_e32 v46, v50, v46
	v_max_f32_e32 v50, v47, v47
	v_mul_f32_e64 v47, |v47|, s43
	v_exp_f32_e32 v47, v47
	v_min_f32_e32 v50, 0, v50
	v_add_f32_e32 v47, 1.0, v47
	v_log_f32_e32 v47, v47
	s_nop 0
	v_mul_f32_e32 v51, 0x3f317217, v47
	v_fma_f32 v51, v47, s44, -v51
	v_fmac_f32_e32 v51, 0x3377d1cf, v47
	v_fmac_f32_e32 v51, 0x3f317217, v47
	v_mov_b32_e32 v47, v51
	v_sub_f32_e32 v47, v50, v47
	v_add_f32_e32 v47, v47, v75
	v_max_f32_e32 v50, v63, v47
	v_sub_f32_e32 v47, v74, v47
	v_mul_f32_e64 v47, |v47|, s43
	v_exp_f32_e32 v47, v47
	s_nop 0
	v_add_f32_e32 v47, 1.0, v47
	v_log_f32_e32 v47, v47
	s_nop 0
	v_mul_f32_e32 v51, 0x3f317217, v47
	v_fma_f32 v51, v47, s44, -v51
	v_fmac_f32_e32 v51, 0x3377d1cf, v47
	v_fmac_f32_e32 v51, 0x3f317217, v47
	v_mov_b32_e32 v47, v51
	v_add_f32_e32 v47, v50, v47
	v_max_f32_e32 v50, v40, v40
	v_mul_f32_e64 v40, |v40|, s43
	v_exp_f32_e32 v40, v40
	v_min_f32_e32 v50, 0, v50
	v_add_f32_e32 v40, 1.0, v40
	v_log_f32_e32 v40, v40
	s_nop 0
	v_mul_f32_e32 v51, 0x3f317217, v40
	v_fma_f32 v51, v40, s44, -v51
	v_fmac_f32_e32 v51, 0x3377d1cf, v40
	v_fmac_f32_e32 v51, 0x3f317217, v40
	v_mov_b32_e32 v40, v51
	v_sub_f32_e32 v40, v50, v40
	v_add_f32_e32 v40, v40, v69
	v_max_f32_e32 v50, v86, v40
	v_sub_f32_e32 v40, v68, v40
	v_mul_f32_e64 v40, |v40|, s43
	v_exp_f32_e32 v40, v40
	s_nop 0
	v_add_f32_e32 v40, 1.0, v40
	v_log_f32_e32 v40, v40
	s_nop 0
	v_mul_f32_e32 v51, 0x3f317217, v40
	v_fma_f32 v51, v40, s44, -v51
	v_fmac_f32_e32 v51, 0x3377d1cf, v40
	v_fmac_f32_e32 v51, 0x3f317217, v40
	v_mov_b32_e32 v40, v51
	v_add_f32_e32 v50, v50, v40
	v_max_f32_e32 v40, v41, v41
	v_mul_f32_e64 v41, |v41|, s43
	v_exp_f32_e32 v41, v41
	v_min_f32_e32 v40, 0, v40
	v_add_f32_e32 v41, 1.0, v41
	v_log_f32_e32 v41, v41
	s_nop 0
	v_mul_f32_e32 v51, 0x3f317217, v41
	v_fma_f32 v51, v41, s44, -v51
	v_fmac_f32_e32 v51, 0x3377d1cf, v41
	v_fmac_f32_e32 v51, 0x3f317217, v41
	v_mov_b32_e32 v41, v51
	v_sub_f32_e32 v40, v40, v41
	v_add_f32_e32 v40, v40, v71
	v_max_f32_e32 v41, v87, v40
	v_sub_f32_e32 v40, v70, v40
	v_mul_f32_e64 v40, |v40|, s43
	v_exp_f32_e32 v40, v40
	s_nop 0
	v_add_f32_e32 v40, 1.0, v40
	v_log_f32_e32 v40, v40
	s_nop 0
	v_mul_f32_e32 v51, 0x3f317217, v40
	v_fma_f32 v51, v40, s44, -v51
	v_fmac_f32_e32 v51, 0x3377d1cf, v40
	v_fmac_f32_e32 v51, 0x3f317217, v40
	v_mov_b32_e32 v40, v51
	v_add_f32_e32 v51, v41, v40
	v_mul_f32_e64 v41, |v42|, s43
	v_exp_f32_e32 v41, v41
	v_max_f32_e32 v40, v42, v42
	v_min_f32_e32 v40, 0, v40
	v_add_f32_e32 v41, 1.0, v41
	v_log_f32_e32 v41, v41
	s_nop 0
	v_mul_f32_e32 v42, 0x3f317217, v41
	v_fma_f32 v42, v41, s44, -v42
	v_fmac_f32_e32 v42, 0x3377d1cf, v41
	v_fmac_f32_e32 v42, 0x3f317217, v41
	v_mov_b32_e32 v41, v42
	v_sub_f32_e32 v40, v40, v41
	v_add_f32_e32 v40, v40, v65
	v_max_f32_e32 v41, v58, v40
	v_sub_f32_e32 v40, v64, v40
	v_mul_f32_e64 v40, |v40|, s43
	v_exp_f32_e32 v40, v40
	s_nop 0
	v_add_f32_e32 v40, 1.0, v40
	v_log_f32_e32 v40, v40
	s_nop 0
	v_mul_f32_e32 v42, 0x3f317217, v40
	v_fma_f32 v42, v40, s44, -v42
	v_fmac_f32_e32 v42, 0x3377d1cf, v40
	v_fmac_f32_e32 v42, 0x3f317217, v40
	v_mov_b32_e32 v40, v42
	v_add_f32_e32 v52, v41, v40
	v_mul_f32_e64 v41, |v43|, s43
	v_exp_f32_e32 v41, v41
	v_max_f32_e32 v40, v43, v43
	v_min_f32_e32 v40, 0, v40
	v_add_f32_e32 v41, 1.0, v41
	v_log_f32_e32 v41, v41
	s_nop 0
	v_mul_f32_e32 v42, 0x3f317217, v41
	v_fma_f32 v42, v41, s44, -v42
	v_fmac_f32_e32 v42, 0x3377d1cf, v41
	v_fmac_f32_e32 v42, 0x3f317217, v41
	v_mov_b32_e32 v41, v42
	v_sub_f32_e32 v40, v40, v41
	v_add_f32_e32 v40, v40, v67
	v_max_f32_e32 v41, v59, v40
	v_sub_f32_e32 v40, v66, v40
	v_mul_f32_e64 v40, |v40|, s43
	v_exp_f32_e32 v40, v40
	s_nop 0
	v_add_f32_e32 v40, 1.0, v40
	v_log_f32_e32 v40, v40
	s_nop 0
	v_mul_f32_e32 v42, 0x3f317217, v40
	v_fma_f32 v42, v40, s44, -v42
	v_fmac_f32_e32 v42, 0x3377d1cf, v40
	v_fmac_f32_e32 v42, 0x3f317217, v40
	v_mov_b32_e32 v40, v42
	v_add_f32_e32 v43, v41, v40
	v_cvt_pk_f16_f32 v40, v44, v45
	v_add_co_u32_e32 v44, vcc, s20, v48
	v_cvt_pk_f16_f32 v41, v46, v47
	v_cvt_pk_f16_f32 v42, v50, v51
	v_cvt_pk_f16_f32 v43, v52, v43
	v_addc_co_u32_e32 v45, vcc, 0, v49, vcc
	global_store_dwordx4 v[44:45], v[40:43], off offset:256
	s_nop 1
	v_max_f32_e32 v42, v36, v36
	v_mul_f32_e64 v36, |v36|, s43
	v_exp_f32_e32 v36, v36
	v_min_f32_e32 v42, 0, v42
	v_lshl_add_u64 v[40:41], s[90:91], 0, v[120:121]
	v_lshl_add_u64 v[40:41], v[40:41], 0, v[208:209]
	v_add_f32_e32 v36, 1.0, v36
	v_log_f32_e32 v36, v36
	s_nop 0
	v_mul_f32_e32 v43, 0x3f317217, v36
	v_fma_f32 v43, v36, s44, -v43
	v_fmac_f32_e32 v43, 0x3377d1cf, v36
	v_fmac_f32_e32 v43, 0x3f317217, v36
	v_mov_b32_e32 v36, v43
	v_sub_f32_e32 v36, v42, v36
	v_add_f32_e32 v36, v36, v77
	v_max_f32_e32 v42, v60, v36
	v_sub_f32_e32 v36, v76, v36
	v_mul_f32_e64 v36, |v36|, s43
	v_exp_f32_e32 v36, v36
	s_nop 0
	v_add_f32_e32 v36, 1.0, v36
	v_log_f32_e32 v36, v36
	s_nop 0
	v_mul_f32_e32 v43, 0x3f317217, v36
	v_fma_f32 v43, v36, s44, -v43
	v_fmac_f32_e32 v43, 0x3377d1cf, v36
	v_fmac_f32_e32 v43, 0x3f317217, v36
	v_mov_b32_e32 v36, v43
	v_add_f32_e32 v36, v42, v36
	v_max_f32_e32 v42, v37, v37
	v_mul_f32_e64 v37, |v37|, s43
	v_exp_f32_e32 v37, v37
	v_min_f32_e32 v42, 0, v42
	v_add_f32_e32 v37, 1.0, v37
	v_log_f32_e32 v37, v37
	s_nop 0
	v_mul_f32_e32 v43, 0x3f317217, v37
	v_fma_f32 v43, v37, s44, -v43
	v_fmac_f32_e32 v43, 0x3377d1cf, v37
	v_fmac_f32_e32 v43, 0x3f317217, v37
	v_mov_b32_e32 v37, v43
	v_sub_f32_e32 v37, v42, v37
	v_add_f32_e32 v37, v37, v79
	v_max_f32_e32 v42, v61, v37
	v_sub_f32_e32 v37, v78, v37
	v_mul_f32_e64 v37, |v37|, s43
	v_exp_f32_e32 v37, v37
	s_nop 0
	v_add_f32_e32 v37, 1.0, v37
	v_log_f32_e32 v37, v37
	s_nop 0
	v_mul_f32_e32 v43, 0x3f317217, v37
	v_fma_f32 v43, v37, s44, -v43
	v_fmac_f32_e32 v43, 0x3377d1cf, v37
	v_fmac_f32_e32 v43, 0x3f317217, v37
	v_mov_b32_e32 v37, v43
	v_add_f32_e32 v37, v42, v37
	v_max_f32_e32 v42, v38, v38
	v_mul_f32_e64 v38, |v38|, s43
	v_exp_f32_e32 v38, v38
	v_min_f32_e32 v42, 0, v42
	v_add_f32_e32 v38, 1.0, v38
	v_log_f32_e32 v38, v38
	s_nop 0
	v_mul_f32_e32 v43, 0x3f317217, v38
	v_fma_f32 v43, v38, s44, -v43
	v_fmac_f32_e32 v43, 0x3377d1cf, v38
	v_fmac_f32_e32 v43, 0x3f317217, v38
	v_mov_b32_e32 v38, v43
	v_sub_f32_e32 v38, v42, v38
	v_add_f32_e32 v38, v38, v73
	v_max_f32_e32 v42, v62, v38
	v_sub_f32_e32 v38, v72, v38
	v_mul_f32_e64 v38, |v38|, s43
	v_exp_f32_e32 v38, v38
	s_nop 0
	v_add_f32_e32 v38, 1.0, v38
	v_log_f32_e32 v38, v38
	s_nop 0
	v_mul_f32_e32 v43, 0x3f317217, v38
	v_fma_f32 v43, v38, s44, -v43
	v_fmac_f32_e32 v43, 0x3377d1cf, v38
	v_fmac_f32_e32 v43, 0x3f317217, v38
	v_mov_b32_e32 v38, v43
	v_add_f32_e32 v38, v42, v38
	v_max_f32_e32 v42, v39, v39
	v_mul_f32_e64 v39, |v39|, s43
	v_exp_f32_e32 v39, v39
	v_min_f32_e32 v42, 0, v42
	v_add_f32_e32 v39, 1.0, v39
	v_log_f32_e32 v39, v39
	s_nop 0
	v_mul_f32_e32 v43, 0x3f317217, v39
	v_fma_f32 v43, v39, s44, -v43
	v_fmac_f32_e32 v43, 0x3377d1cf, v39
	v_fmac_f32_e32 v43, 0x3f317217, v39
	v_mov_b32_e32 v39, v43
	v_sub_f32_e32 v39, v42, v39
	v_add_f32_e32 v39, v39, v75
	v_max_f32_e32 v42, v63, v39
	v_sub_f32_e32 v39, v74, v39
	v_mul_f32_e64 v39, |v39|, s43
	v_exp_f32_e32 v39, v39
	s_nop 0
	v_add_f32_e32 v39, 1.0, v39
	v_log_f32_e32 v39, v39
	s_nop 0
	v_mul_f32_e32 v43, 0x3f317217, v39
	v_fma_f32 v43, v39, s44, -v43
	v_fmac_f32_e32 v43, 0x3377d1cf, v39
	v_fmac_f32_e32 v43, 0x3f317217, v39
	v_mov_b32_e32 v39, v43
	v_add_f32_e32 v39, v42, v39
	v_max_f32_e32 v42, v32, v32
	v_mul_f32_e64 v32, |v32|, s43
	v_exp_f32_e32 v32, v32
	v_min_f32_e32 v42, 0, v42
	v_add_f32_e32 v32, 1.0, v32
	v_log_f32_e32 v32, v32
	s_nop 0
	v_mul_f32_e32 v43, 0x3f317217, v32
	v_fma_f32 v43, v32, s44, -v43
	v_fmac_f32_e32 v43, 0x3377d1cf, v32
	v_fmac_f32_e32 v43, 0x3f317217, v32
	v_mov_b32_e32 v32, v43
	v_sub_f32_e32 v32, v42, v32
	v_add_f32_e32 v32, v32, v69
	v_max_f32_e32 v42, v86, v32
	v_sub_f32_e32 v32, v68, v32
	v_mul_f32_e64 v32, |v32|, s43
	v_exp_f32_e32 v32, v32
	s_nop 0
	v_add_f32_e32 v32, 1.0, v32
	v_log_f32_e32 v32, v32
	s_nop 0
	v_mul_f32_e32 v43, 0x3f317217, v32
	v_fma_f32 v43, v32, s44, -v43
	v_fmac_f32_e32 v43, 0x3377d1cf, v32
	v_fmac_f32_e32 v43, 0x3f317217, v32
	v_mov_b32_e32 v32, v43
	v_add_f32_e32 v42, v42, v32
	v_max_f32_e32 v32, v33, v33
	v_mul_f32_e64 v33, |v33|, s43
	v_exp_f32_e32 v33, v33
	v_min_f32_e32 v32, 0, v32
	v_add_f32_e32 v33, 1.0, v33
	v_log_f32_e32 v33, v33
	s_nop 0
	v_mul_f32_e32 v43, 0x3f317217, v33
	v_fma_f32 v43, v33, s44, -v43
	v_fmac_f32_e32 v43, 0x3377d1cf, v33
	v_fmac_f32_e32 v43, 0x3f317217, v33
	v_mov_b32_e32 v33, v43
	v_sub_f32_e32 v32, v32, v33
	v_add_f32_e32 v32, v32, v71
	v_max_f32_e32 v33, v87, v32
	v_sub_f32_e32 v32, v70, v32
	v_mul_f32_e64 v32, |v32|, s43
	v_exp_f32_e32 v32, v32
	s_nop 0
	v_add_f32_e32 v32, 1.0, v32
	v_log_f32_e32 v32, v32
	s_nop 0
	v_mul_f32_e32 v43, 0x3f317217, v32
	v_fma_f32 v43, v32, s44, -v43
	v_fmac_f32_e32 v43, 0x3377d1cf, v32
	v_fmac_f32_e32 v43, 0x3f317217, v32
	v_mov_b32_e32 v32, v43
	v_add_f32_e32 v43, v33, v32
	v_mul_f32_e64 v33, |v34|, s43
	v_exp_f32_e32 v33, v33
	v_max_f32_e32 v32, v34, v34
	v_min_f32_e32 v32, 0, v32
	v_add_f32_e32 v33, 1.0, v33
	v_log_f32_e32 v33, v33
	s_nop 0
	v_mul_f32_e32 v34, 0x3f317217, v33
	v_fma_f32 v34, v33, s44, -v34
	v_fmac_f32_e32 v34, 0x3377d1cf, v33
	v_fmac_f32_e32 v34, 0x3f317217, v33
	v_mov_b32_e32 v33, v34
	v_sub_f32_e32 v32, v32, v33
	v_add_f32_e32 v32, v32, v65
	v_max_f32_e32 v33, v58, v32
	v_sub_f32_e32 v32, v64, v32
	v_mul_f32_e64 v32, |v32|, s43
	v_exp_f32_e32 v32, v32
	s_nop 0
	v_add_f32_e32 v32, 1.0, v32
	v_log_f32_e32 v32, v32
	s_nop 0
	v_mul_f32_e32 v34, 0x3f317217, v32
	v_fma_f32 v34, v32, s44, -v34
	v_fmac_f32_e32 v34, 0x3377d1cf, v32
	v_fmac_f32_e32 v34, 0x3f317217, v32
	v_mov_b32_e32 v32, v34
	v_add_f32_e32 v44, v33, v32
	v_mul_f32_e64 v33, |v35|, s43
	v_exp_f32_e32 v33, v33
	v_max_f32_e32 v32, v35, v35
	v_min_f32_e32 v32, 0, v32
	v_add_f32_e32 v33, 1.0, v33
	v_log_f32_e32 v33, v33
	s_nop 0
	v_mul_f32_e32 v34, 0x3f317217, v33
	v_fma_f32 v34, v33, s44, -v34
	v_fmac_f32_e32 v34, 0x3377d1cf, v33
	v_fmac_f32_e32 v34, 0x3f317217, v33
	v_mov_b32_e32 v33, v34
	v_sub_f32_e32 v32, v32, v33
	v_add_f32_e32 v32, v32, v67
	v_max_f32_e32 v33, v59, v32
	v_sub_f32_e32 v32, v66, v32
	v_mul_f32_e64 v32, |v32|, s43
	v_exp_f32_e32 v32, v32
	s_nop 0
	v_add_f32_e32 v32, 1.0, v32
	v_log_f32_e32 v32, v32
	s_nop 0
	v_mul_f32_e32 v34, 0x3f317217, v32
	v_fma_f32 v34, v32, s44, -v34
	v_fmac_f32_e32 v34, 0x3377d1cf, v32
	v_fmac_f32_e32 v34, 0x3f317217, v32
	v_mov_b32_e32 v32, v34
	v_add_f32_e32 v35, v33, v32
	v_cvt_pk_f16_f32 v32, v36, v37
	v_add_co_u32_e32 v36, vcc, s20, v40
	v_cvt_pk_f16_f32 v33, v38, v39
	v_cvt_pk_f16_f32 v34, v42, v43
	v_cvt_pk_f16_f32 v35, v44, v35
	v_addc_co_u32_e32 v37, vcc, 0, v41, vcc
	global_store_dwordx4 v[36:37], v[32:35], off offset:256
	s_nop 1
	v_max_f32_e32 v34, v28, v28
	v_mul_f32_e64 v28, |v28|, s43
	v_exp_f32_e32 v28, v28
	v_min_f32_e32 v34, 0, v34
	v_lshl_add_u64 v[32:33], s[90:91], 0, v[112:113]
	v_lshl_add_u64 v[32:33], v[32:33], 0, v[208:209]
	v_add_f32_e32 v28, 1.0, v28
	v_log_f32_e32 v28, v28
	s_nop 0
	v_mul_f32_e32 v35, 0x3f317217, v28
	v_fma_f32 v35, v28, s44, -v35
	v_fmac_f32_e32 v35, 0x3377d1cf, v28
	v_fmac_f32_e32 v35, 0x3f317217, v28
	v_mov_b32_e32 v28, v35
	v_sub_f32_e32 v28, v34, v28
	v_add_f32_e32 v28, v28, v77
	v_max_f32_e32 v34, v60, v28
	v_sub_f32_e32 v28, v76, v28
	v_mul_f32_e64 v28, |v28|, s43
	v_exp_f32_e32 v28, v28
	s_nop 0
	v_add_f32_e32 v28, 1.0, v28
	v_log_f32_e32 v28, v28
	s_nop 0
	v_mul_f32_e32 v35, 0x3f317217, v28
	v_fma_f32 v35, v28, s44, -v35
	v_fmac_f32_e32 v35, 0x3377d1cf, v28
	v_fmac_f32_e32 v35, 0x3f317217, v28
	v_mov_b32_e32 v28, v35
	v_add_f32_e32 v28, v34, v28
	v_max_f32_e32 v34, v29, v29
	v_mul_f32_e64 v29, |v29|, s43
	v_exp_f32_e32 v29, v29
	v_min_f32_e32 v34, 0, v34
	v_add_f32_e32 v29, 1.0, v29
	v_log_f32_e32 v29, v29
	s_nop 0
	v_mul_f32_e32 v35, 0x3f317217, v29
	v_fma_f32 v35, v29, s44, -v35
	v_fmac_f32_e32 v35, 0x3377d1cf, v29
	v_fmac_f32_e32 v35, 0x3f317217, v29
	v_mov_b32_e32 v29, v35
	v_sub_f32_e32 v29, v34, v29
	v_add_f32_e32 v29, v29, v79
	v_max_f32_e32 v34, v61, v29
	v_sub_f32_e32 v29, v78, v29
	v_mul_f32_e64 v29, |v29|, s43
	v_exp_f32_e32 v29, v29
	s_nop 0
	v_add_f32_e32 v29, 1.0, v29
	v_log_f32_e32 v29, v29
	s_nop 0
	v_mul_f32_e32 v35, 0x3f317217, v29
	v_fma_f32 v35, v29, s44, -v35
	v_fmac_f32_e32 v35, 0x3377d1cf, v29
	v_fmac_f32_e32 v35, 0x3f317217, v29
	v_mov_b32_e32 v29, v35
	v_add_f32_e32 v29, v34, v29
	v_max_f32_e32 v34, v30, v30
	v_mul_f32_e64 v30, |v30|, s43
	v_exp_f32_e32 v30, v30
	v_min_f32_e32 v34, 0, v34
	v_add_f32_e32 v30, 1.0, v30
	v_log_f32_e32 v30, v30
	s_nop 0
	v_mul_f32_e32 v35, 0x3f317217, v30
	v_fma_f32 v35, v30, s44, -v35
	v_fmac_f32_e32 v35, 0x3377d1cf, v30
	v_fmac_f32_e32 v35, 0x3f317217, v30
	v_mov_b32_e32 v30, v35
	v_sub_f32_e32 v30, v34, v30
	v_add_f32_e32 v30, v30, v73
	v_max_f32_e32 v34, v62, v30
	v_sub_f32_e32 v30, v72, v30
	v_mul_f32_e64 v30, |v30|, s43
	v_exp_f32_e32 v30, v30
	s_nop 0
	v_add_f32_e32 v30, 1.0, v30
	v_log_f32_e32 v30, v30
	s_nop 0
	v_mul_f32_e32 v35, 0x3f317217, v30
	v_fma_f32 v35, v30, s44, -v35
	v_fmac_f32_e32 v35, 0x3377d1cf, v30
	v_fmac_f32_e32 v35, 0x3f317217, v30
	v_mov_b32_e32 v30, v35
	v_add_f32_e32 v30, v34, v30
	v_max_f32_e32 v34, v31, v31
	v_mul_f32_e64 v31, |v31|, s43
	v_exp_f32_e32 v31, v31
	v_min_f32_e32 v34, 0, v34
	v_add_f32_e32 v31, 1.0, v31
	v_log_f32_e32 v31, v31
	s_nop 0
	v_mul_f32_e32 v35, 0x3f317217, v31
	v_fma_f32 v35, v31, s44, -v35
	v_fmac_f32_e32 v35, 0x3377d1cf, v31
	v_fmac_f32_e32 v35, 0x3f317217, v31
	v_mov_b32_e32 v31, v35
	v_sub_f32_e32 v31, v34, v31
	v_add_f32_e32 v31, v31, v75
	v_max_f32_e32 v34, v63, v31
	v_sub_f32_e32 v31, v74, v31
	v_mul_f32_e64 v31, |v31|, s43
	v_exp_f32_e32 v31, v31
	s_nop 0
	v_add_f32_e32 v31, 1.0, v31
	v_log_f32_e32 v31, v31
	s_nop 0
	v_mul_f32_e32 v35, 0x3f317217, v31
	v_fma_f32 v35, v31, s44, -v35
	v_fmac_f32_e32 v35, 0x3377d1cf, v31
	v_fmac_f32_e32 v35, 0x3f317217, v31
	v_mov_b32_e32 v31, v35
	v_add_f32_e32 v31, v34, v31
	v_max_f32_e32 v34, v24, v24
	v_mul_f32_e64 v24, |v24|, s43
	v_exp_f32_e32 v24, v24
	v_min_f32_e32 v34, 0, v34
	v_add_f32_e32 v24, 1.0, v24
	v_log_f32_e32 v24, v24
	s_nop 0
	v_mul_f32_e32 v35, 0x3f317217, v24
	v_fma_f32 v35, v24, s44, -v35
	v_fmac_f32_e32 v35, 0x3377d1cf, v24
	v_fmac_f32_e32 v35, 0x3f317217, v24
	v_mov_b32_e32 v24, v35
	v_sub_f32_e32 v24, v34, v24
	v_add_f32_e32 v24, v24, v69
	v_max_f32_e32 v34, v86, v24
	v_sub_f32_e32 v24, v68, v24
	v_mul_f32_e64 v24, |v24|, s43
	v_exp_f32_e32 v24, v24
	s_nop 0
	v_add_f32_e32 v24, 1.0, v24
	v_log_f32_e32 v24, v24
	s_nop 0
	v_mul_f32_e32 v35, 0x3f317217, v24
	v_fma_f32 v35, v24, s44, -v35
	v_fmac_f32_e32 v35, 0x3377d1cf, v24
	v_fmac_f32_e32 v35, 0x3f317217, v24
	v_mov_b32_e32 v24, v35
	v_add_f32_e32 v34, v34, v24
	v_max_f32_e32 v24, v25, v25
	v_mul_f32_e64 v25, |v25|, s43
	v_exp_f32_e32 v25, v25
	v_min_f32_e32 v24, 0, v24
	v_add_f32_e32 v25, 1.0, v25
	v_log_f32_e32 v25, v25
	s_nop 0
	v_mul_f32_e32 v35, 0x3f317217, v25
	v_fma_f32 v35, v25, s44, -v35
	v_fmac_f32_e32 v35, 0x3377d1cf, v25
	v_fmac_f32_e32 v35, 0x3f317217, v25
	v_mov_b32_e32 v25, v35
	v_sub_f32_e32 v24, v24, v25
	v_add_f32_e32 v24, v24, v71
	v_max_f32_e32 v25, v87, v24
	v_sub_f32_e32 v24, v70, v24
	v_mul_f32_e64 v24, |v24|, s43
	v_exp_f32_e32 v24, v24
	s_nop 0
	v_add_f32_e32 v24, 1.0, v24
	v_log_f32_e32 v24, v24
	s_nop 0
	v_mul_f32_e32 v35, 0x3f317217, v24
	v_fma_f32 v35, v24, s44, -v35
	v_fmac_f32_e32 v35, 0x3377d1cf, v24
	v_fmac_f32_e32 v35, 0x3f317217, v24
	v_mov_b32_e32 v24, v35
	v_add_f32_e32 v35, v25, v24
	v_mul_f32_e64 v25, |v26|, s43
	v_exp_f32_e32 v25, v25
	v_max_f32_e32 v24, v26, v26
	v_min_f32_e32 v24, 0, v24
	v_add_f32_e32 v25, 1.0, v25
	v_log_f32_e32 v25, v25
	s_nop 0
	v_mul_f32_e32 v26, 0x3f317217, v25
	v_fma_f32 v26, v25, s44, -v26
	v_fmac_f32_e32 v26, 0x3377d1cf, v25
	v_fmac_f32_e32 v26, 0x3f317217, v25
	v_mov_b32_e32 v25, v26
	v_sub_f32_e32 v24, v24, v25
	v_add_f32_e32 v24, v24, v65
	v_max_f32_e32 v25, v58, v24
	v_sub_f32_e32 v24, v64, v24
	v_mul_f32_e64 v24, |v24|, s43
	v_exp_f32_e32 v24, v24
	s_nop 0
	v_add_f32_e32 v24, 1.0, v24
	v_log_f32_e32 v24, v24
	s_nop 0
	v_mul_f32_e32 v26, 0x3f317217, v24
	v_fma_f32 v26, v24, s44, -v26
	v_fmac_f32_e32 v26, 0x3377d1cf, v24
	v_fmac_f32_e32 v26, 0x3f317217, v24
	v_mov_b32_e32 v24, v26
	v_add_f32_e32 v36, v25, v24
	v_mul_f32_e64 v25, |v27|, s43
	v_exp_f32_e32 v25, v25
	v_max_f32_e32 v24, v27, v27
	v_min_f32_e32 v24, 0, v24
	v_add_f32_e32 v25, 1.0, v25
	v_log_f32_e32 v25, v25
	s_nop 0
	v_mul_f32_e32 v26, 0x3f317217, v25
	v_fma_f32 v26, v25, s44, -v26
	v_fmac_f32_e32 v26, 0x3377d1cf, v25
	v_fmac_f32_e32 v26, 0x3f317217, v25
	v_mov_b32_e32 v25, v26
	v_sub_f32_e32 v24, v24, v25
	v_add_f32_e32 v24, v24, v67
	v_max_f32_e32 v25, v59, v24
	v_sub_f32_e32 v24, v66, v24
	v_mul_f32_e64 v24, |v24|, s43
	v_exp_f32_e32 v24, v24
	s_nop 0
	v_add_f32_e32 v24, 1.0, v24
	v_log_f32_e32 v24, v24
	s_nop 0
	v_mul_f32_e32 v26, 0x3f317217, v24
	v_fma_f32 v26, v24, s44, -v26
	v_fmac_f32_e32 v26, 0x3377d1cf, v24
	v_fmac_f32_e32 v26, 0x3f317217, v24
	v_mov_b32_e32 v24, v26
	v_add_f32_e32 v27, v25, v24
	v_cvt_pk_f16_f32 v24, v28, v29
	v_add_co_u32_e32 v28, vcc, s20, v32
	v_cvt_pk_f16_f32 v25, v30, v31
	v_cvt_pk_f16_f32 v26, v34, v35
	v_cvt_pk_f16_f32 v27, v36, v27
	v_addc_co_u32_e32 v29, vcc, 0, v33, vcc
	global_store_dwordx4 v[28:29], v[24:27], off offset:256
	s_nop 1
	v_max_f32_e32 v26, v20, v20
	v_mul_f32_e64 v20, |v20|, s43
	v_exp_f32_e32 v20, v20
	v_min_f32_e32 v26, 0, v26
	v_lshl_add_u64 v[24:25], s[90:91], 0, v[104:105]
	v_lshl_add_u64 v[24:25], v[24:25], 0, v[208:209]
	v_add_f32_e32 v20, 1.0, v20
	v_log_f32_e32 v20, v20
	s_nop 0
	v_mul_f32_e32 v27, 0x3f317217, v20
	v_fma_f32 v27, v20, s44, -v27
	v_fmac_f32_e32 v27, 0x3377d1cf, v20
	v_fmac_f32_e32 v27, 0x3f317217, v20
	v_mov_b32_e32 v20, v27
	v_sub_f32_e32 v20, v26, v20
	v_add_f32_e32 v20, v20, v77
	v_max_f32_e32 v26, v60, v20
	v_sub_f32_e32 v20, v76, v20
	v_mul_f32_e64 v20, |v20|, s43
	v_exp_f32_e32 v20, v20
	s_nop 0
	v_add_f32_e32 v20, 1.0, v20
	v_log_f32_e32 v20, v20
	s_nop 0
	v_mul_f32_e32 v27, 0x3f317217, v20
	v_fma_f32 v27, v20, s44, -v27
	v_fmac_f32_e32 v27, 0x3377d1cf, v20
	v_fmac_f32_e32 v27, 0x3f317217, v20
	v_mov_b32_e32 v20, v27
	v_add_f32_e32 v20, v26, v20
	v_max_f32_e32 v26, v21, v21
	v_mul_f32_e64 v21, |v21|, s43
	v_exp_f32_e32 v21, v21
	v_min_f32_e32 v26, 0, v26
	v_add_f32_e32 v21, 1.0, v21
	v_log_f32_e32 v21, v21
	s_nop 0
	v_mul_f32_e32 v27, 0x3f317217, v21
	v_fma_f32 v27, v21, s44, -v27
	v_fmac_f32_e32 v27, 0x3377d1cf, v21
	v_fmac_f32_e32 v27, 0x3f317217, v21
	v_mov_b32_e32 v21, v27
	v_sub_f32_e32 v21, v26, v21
	v_add_f32_e32 v21, v21, v79
	v_max_f32_e32 v26, v61, v21
	v_sub_f32_e32 v21, v78, v21
	v_mul_f32_e64 v21, |v21|, s43
	v_exp_f32_e32 v21, v21
	s_nop 0
	v_add_f32_e32 v21, 1.0, v21
	v_log_f32_e32 v21, v21
	s_nop 0
	v_mul_f32_e32 v27, 0x3f317217, v21
	v_fma_f32 v27, v21, s44, -v27
	v_fmac_f32_e32 v27, 0x3377d1cf, v21
	v_fmac_f32_e32 v27, 0x3f317217, v21
	v_mov_b32_e32 v21, v27
	v_add_f32_e32 v21, v26, v21
	v_max_f32_e32 v26, v22, v22
	v_mul_f32_e64 v22, |v22|, s43
	v_exp_f32_e32 v22, v22
	v_min_f32_e32 v26, 0, v26
	v_add_f32_e32 v22, 1.0, v22
	v_log_f32_e32 v22, v22
	s_nop 0
	v_mul_f32_e32 v27, 0x3f317217, v22
	v_fma_f32 v27, v22, s44, -v27
	v_fmac_f32_e32 v27, 0x3377d1cf, v22
	v_fmac_f32_e32 v27, 0x3f317217, v22
	v_mov_b32_e32 v22, v27
	v_sub_f32_e32 v22, v26, v22
	v_add_f32_e32 v22, v22, v73
	v_max_f32_e32 v26, v62, v22
	v_sub_f32_e32 v22, v72, v22
	v_mul_f32_e64 v22, |v22|, s43
	v_exp_f32_e32 v22, v22
	s_nop 0
	v_add_f32_e32 v22, 1.0, v22
	v_log_f32_e32 v22, v22
	s_nop 0
	v_mul_f32_e32 v27, 0x3f317217, v22
	v_fma_f32 v27, v22, s44, -v27
	v_fmac_f32_e32 v27, 0x3377d1cf, v22
	v_fmac_f32_e32 v27, 0x3f317217, v22
	v_mov_b32_e32 v22, v27
	v_add_f32_e32 v22, v26, v22
	v_max_f32_e32 v26, v23, v23
	v_mul_f32_e64 v23, |v23|, s43
	v_exp_f32_e32 v23, v23
	v_min_f32_e32 v26, 0, v26
	v_add_f32_e32 v23, 1.0, v23
	v_log_f32_e32 v23, v23
	s_nop 0
	v_mul_f32_e32 v27, 0x3f317217, v23
	v_fma_f32 v27, v23, s44, -v27
	v_fmac_f32_e32 v27, 0x3377d1cf, v23
	v_fmac_f32_e32 v27, 0x3f317217, v23
	v_mov_b32_e32 v23, v27
	v_sub_f32_e32 v23, v26, v23
	v_add_f32_e32 v23, v23, v75
	v_max_f32_e32 v26, v63, v23
	v_sub_f32_e32 v23, v74, v23
	v_mul_f32_e64 v23, |v23|, s43
	v_exp_f32_e32 v23, v23
	s_nop 0
	v_add_f32_e32 v23, 1.0, v23
	v_log_f32_e32 v23, v23
	s_nop 0
	v_mul_f32_e32 v27, 0x3f317217, v23
	v_fma_f32 v27, v23, s44, -v27
	v_fmac_f32_e32 v27, 0x3377d1cf, v23
	v_fmac_f32_e32 v27, 0x3f317217, v23
	v_mov_b32_e32 v23, v27
	v_add_f32_e32 v23, v26, v23
	v_max_f32_e32 v26, v16, v16
	v_mul_f32_e64 v16, |v16|, s43
	v_exp_f32_e32 v16, v16
	v_min_f32_e32 v26, 0, v26
	v_add_f32_e32 v16, 1.0, v16
	v_log_f32_e32 v16, v16
	s_nop 0
	v_mul_f32_e32 v27, 0x3f317217, v16
	v_fma_f32 v27, v16, s44, -v27
	v_fmac_f32_e32 v27, 0x3377d1cf, v16
	v_fmac_f32_e32 v27, 0x3f317217, v16
	v_mov_b32_e32 v16, v27
	v_sub_f32_e32 v16, v26, v16
	v_add_f32_e32 v16, v16, v69
	v_max_f32_e32 v26, v86, v16
	v_sub_f32_e32 v16, v68, v16
	v_mul_f32_e64 v16, |v16|, s43
	v_exp_f32_e32 v16, v16
	s_nop 0
	v_add_f32_e32 v16, 1.0, v16
	v_log_f32_e32 v16, v16
	s_nop 0
	v_mul_f32_e32 v27, 0x3f317217, v16
	v_fma_f32 v27, v16, s44, -v27
	v_fmac_f32_e32 v27, 0x3377d1cf, v16
	v_fmac_f32_e32 v27, 0x3f317217, v16
	v_mov_b32_e32 v16, v27
	v_add_f32_e32 v26, v26, v16
	v_max_f32_e32 v16, v17, v17
	v_mul_f32_e64 v17, |v17|, s43
	v_exp_f32_e32 v17, v17
	v_min_f32_e32 v16, 0, v16
	v_add_f32_e32 v17, 1.0, v17
	v_log_f32_e32 v17, v17
	s_nop 0
	v_mul_f32_e32 v27, 0x3f317217, v17
	v_fma_f32 v27, v17, s44, -v27
	v_fmac_f32_e32 v27, 0x3377d1cf, v17
	v_fmac_f32_e32 v27, 0x3f317217, v17
	v_mov_b32_e32 v17, v27
	v_sub_f32_e32 v16, v16, v17
	v_add_f32_e32 v16, v16, v71
	v_max_f32_e32 v17, v87, v16
	v_sub_f32_e32 v16, v70, v16
	v_mul_f32_e64 v16, |v16|, s43
	v_exp_f32_e32 v16, v16
	s_nop 0
	v_add_f32_e32 v16, 1.0, v16
	v_log_f32_e32 v16, v16
	s_nop 0
	v_mul_f32_e32 v27, 0x3f317217, v16
	v_fma_f32 v27, v16, s44, -v27
	v_fmac_f32_e32 v27, 0x3377d1cf, v16
	v_fmac_f32_e32 v27, 0x3f317217, v16
	v_mov_b32_e32 v16, v27
	v_add_f32_e32 v27, v17, v16
	v_mul_f32_e64 v17, |v18|, s43
	v_exp_f32_e32 v17, v17
	v_max_f32_e32 v16, v18, v18
	v_min_f32_e32 v16, 0, v16
	v_add_f32_e32 v17, 1.0, v17
	v_log_f32_e32 v17, v17
	s_nop 0
	v_mul_f32_e32 v18, 0x3f317217, v17
	v_fma_f32 v18, v17, s44, -v18
	v_fmac_f32_e32 v18, 0x3377d1cf, v17
	v_fmac_f32_e32 v18, 0x3f317217, v17
	v_mov_b32_e32 v17, v18
	v_sub_f32_e32 v16, v16, v17
	v_add_f32_e32 v16, v16, v65
	v_max_f32_e32 v17, v58, v16
	v_sub_f32_e32 v16, v64, v16
	v_mul_f32_e64 v16, |v16|, s43
	v_exp_f32_e32 v16, v16
	s_nop 0
	v_add_f32_e32 v16, 1.0, v16
	v_log_f32_e32 v16, v16
	s_nop 0
	v_mul_f32_e32 v18, 0x3f317217, v16
	v_fma_f32 v18, v16, s44, -v18
	v_fmac_f32_e32 v18, 0x3377d1cf, v16
	v_fmac_f32_e32 v18, 0x3f317217, v16
	v_mov_b32_e32 v16, v18
	v_add_f32_e32 v28, v17, v16
	v_mul_f32_e64 v17, |v19|, s43
	v_exp_f32_e32 v17, v17
	v_max_f32_e32 v16, v19, v19
	v_min_f32_e32 v16, 0, v16
	v_add_f32_e32 v17, 1.0, v17
	v_log_f32_e32 v17, v17
	s_nop 0
	v_mul_f32_e32 v18, 0x3f317217, v17
	v_fma_f32 v18, v17, s44, -v18
	v_fmac_f32_e32 v18, 0x3377d1cf, v17
	v_fmac_f32_e32 v18, 0x3f317217, v17
	v_mov_b32_e32 v17, v18
	v_sub_f32_e32 v16, v16, v17
	v_add_f32_e32 v16, v16, v67
	v_max_f32_e32 v17, v59, v16
	v_sub_f32_e32 v16, v66, v16
	v_mul_f32_e64 v16, |v16|, s43
	v_exp_f32_e32 v16, v16
	s_nop 0
	v_add_f32_e32 v16, 1.0, v16
	v_log_f32_e32 v16, v16
	s_nop 0
	v_mul_f32_e32 v18, 0x3f317217, v16
	v_fma_f32 v18, v16, s44, -v18
	v_fmac_f32_e32 v18, 0x3377d1cf, v16
	v_fmac_f32_e32 v18, 0x3f317217, v16
	v_mov_b32_e32 v16, v18
	v_add_f32_e32 v19, v17, v16
	v_cvt_pk_f16_f32 v16, v20, v21
	v_add_co_u32_e32 v20, vcc, s20, v24
	v_cvt_pk_f16_f32 v17, v22, v23
	v_cvt_pk_f16_f32 v18, v26, v27
	v_cvt_pk_f16_f32 v19, v28, v19
	v_addc_co_u32_e32 v21, vcc, 0, v25, vcc
	global_store_dwordx4 v[20:21], v[16:19], off offset:256
	s_nop 1
	v_max_f32_e32 v18, v12, v12
	v_mul_f32_e64 v12, |v12|, s43
	v_exp_f32_e32 v12, v12
	v_min_f32_e32 v18, 0, v18
	v_lshl_add_u64 v[16:17], s[90:91], 0, v[82:83]
	v_lshl_add_u64 v[16:17], v[16:17], 0, v[208:209]
	v_add_f32_e32 v12, 1.0, v12
	v_log_f32_e32 v12, v12
	s_nop 0
	v_mul_f32_e32 v19, 0x3f317217, v12
	v_fma_f32 v19, v12, s44, -v19
	v_fmac_f32_e32 v19, 0x3377d1cf, v12
	v_fmac_f32_e32 v19, 0x3f317217, v12
	v_mov_b32_e32 v12, v19
	v_sub_f32_e32 v12, v18, v12
	v_add_f32_e32 v12, v12, v77
	v_max_f32_e32 v18, v60, v12
	v_sub_f32_e32 v12, v76, v12
	v_mul_f32_e64 v12, |v12|, s43
	v_exp_f32_e32 v12, v12
	s_nop 0
	v_add_f32_e32 v12, 1.0, v12
	v_log_f32_e32 v12, v12
	s_nop 0
	v_mul_f32_e32 v19, 0x3f317217, v12
	v_fma_f32 v19, v12, s44, -v19
	v_fmac_f32_e32 v19, 0x3377d1cf, v12
	v_fmac_f32_e32 v19, 0x3f317217, v12
	v_mov_b32_e32 v12, v19
	v_add_f32_e32 v12, v18, v12
	v_max_f32_e32 v18, v13, v13
	v_mul_f32_e64 v13, |v13|, s43
	v_exp_f32_e32 v13, v13
	v_min_f32_e32 v18, 0, v18
	v_add_f32_e32 v13, 1.0, v13
	v_log_f32_e32 v13, v13
	s_nop 0
	v_mul_f32_e32 v19, 0x3f317217, v13
	v_fma_f32 v19, v13, s44, -v19
	v_fmac_f32_e32 v19, 0x3377d1cf, v13
	v_fmac_f32_e32 v19, 0x3f317217, v13
	v_mov_b32_e32 v13, v19
	v_sub_f32_e32 v13, v18, v13
	v_add_f32_e32 v13, v13, v79
	v_max_f32_e32 v18, v61, v13
	v_sub_f32_e32 v13, v78, v13
	v_mul_f32_e64 v13, |v13|, s43
	v_exp_f32_e32 v13, v13
	s_nop 0
	v_add_f32_e32 v13, 1.0, v13
	v_log_f32_e32 v13, v13
	s_nop 0
	v_mul_f32_e32 v19, 0x3f317217, v13
	v_fma_f32 v19, v13, s44, -v19
	v_fmac_f32_e32 v19, 0x3377d1cf, v13
	v_fmac_f32_e32 v19, 0x3f317217, v13
	v_mov_b32_e32 v13, v19
	v_add_f32_e32 v13, v18, v13
	v_max_f32_e32 v18, v14, v14
	v_mul_f32_e64 v14, |v14|, s43
	v_exp_f32_e32 v14, v14
	v_min_f32_e32 v18, 0, v18
	v_add_f32_e32 v14, 1.0, v14
	v_log_f32_e32 v14, v14
	s_nop 0
	v_mul_f32_e32 v19, 0x3f317217, v14
	v_fma_f32 v19, v14, s44, -v19
	v_fmac_f32_e32 v19, 0x3377d1cf, v14
	v_fmac_f32_e32 v19, 0x3f317217, v14
	v_mov_b32_e32 v14, v19
	v_sub_f32_e32 v14, v18, v14
	v_add_f32_e32 v14, v14, v73
	v_max_f32_e32 v18, v62, v14
	v_sub_f32_e32 v14, v72, v14
	v_mul_f32_e64 v14, |v14|, s43
	v_exp_f32_e32 v14, v14
	s_nop 0
	v_add_f32_e32 v14, 1.0, v14
	v_log_f32_e32 v14, v14
	s_nop 0
	v_mul_f32_e32 v19, 0x3f317217, v14
	v_fma_f32 v19, v14, s44, -v19
	v_fmac_f32_e32 v19, 0x3377d1cf, v14
	v_fmac_f32_e32 v19, 0x3f317217, v14
	v_mov_b32_e32 v14, v19
	v_add_f32_e32 v14, v18, v14
	v_max_f32_e32 v18, v15, v15
	v_mul_f32_e64 v15, |v15|, s43
	v_exp_f32_e32 v15, v15
	v_min_f32_e32 v18, 0, v18
	v_add_f32_e32 v15, 1.0, v15
	v_log_f32_e32 v15, v15
	s_nop 0
	v_mul_f32_e32 v19, 0x3f317217, v15
	v_fma_f32 v19, v15, s44, -v19
	v_fmac_f32_e32 v19, 0x3377d1cf, v15
	v_fmac_f32_e32 v19, 0x3f317217, v15
	v_mov_b32_e32 v15, v19
	v_sub_f32_e32 v15, v18, v15
	v_add_f32_e32 v15, v15, v75
	v_max_f32_e32 v18, v63, v15
	v_sub_f32_e32 v15, v74, v15
	v_mul_f32_e64 v15, |v15|, s43
	v_exp_f32_e32 v15, v15
	s_nop 0
	v_add_f32_e32 v15, 1.0, v15
	v_log_f32_e32 v15, v15
	s_nop 0
	v_mul_f32_e32 v19, 0x3f317217, v15
	v_fma_f32 v19, v15, s44, -v19
	v_fmac_f32_e32 v19, 0x3377d1cf, v15
	v_fmac_f32_e32 v19, 0x3f317217, v15
	v_mov_b32_e32 v15, v19
	v_add_f32_e32 v15, v18, v15
	v_max_f32_e32 v18, v8, v8
	v_mul_f32_e64 v8, |v8|, s43
	v_exp_f32_e32 v8, v8
	v_min_f32_e32 v18, 0, v18
	v_add_f32_e32 v8, 1.0, v8
	v_log_f32_e32 v8, v8
	s_nop 0
	v_mul_f32_e32 v19, 0x3f317217, v8
	v_fma_f32 v19, v8, s44, -v19
	v_fmac_f32_e32 v19, 0x3377d1cf, v8
	v_fmac_f32_e32 v19, 0x3f317217, v8
	v_mov_b32_e32 v8, v19
	v_sub_f32_e32 v8, v18, v8
	v_add_f32_e32 v8, v8, v69
	v_max_f32_e32 v18, v86, v8
	v_sub_f32_e32 v8, v68, v8
	v_mul_f32_e64 v8, |v8|, s43
	v_exp_f32_e32 v8, v8
	s_nop 0
	v_add_f32_e32 v8, 1.0, v8
	v_log_f32_e32 v8, v8
	s_nop 0
	v_mul_f32_e32 v19, 0x3f317217, v8
	v_fma_f32 v19, v8, s44, -v19
	v_fmac_f32_e32 v19, 0x3377d1cf, v8
	v_fmac_f32_e32 v19, 0x3f317217, v8
	v_mov_b32_e32 v8, v19
	v_add_f32_e32 v18, v18, v8
	v_max_f32_e32 v8, v9, v9
	v_mul_f32_e64 v9, |v9|, s43
	v_exp_f32_e32 v9, v9
	v_min_f32_e32 v8, 0, v8
	v_add_f32_e32 v9, 1.0, v9
	v_log_f32_e32 v9, v9
	s_nop 0
	v_mul_f32_e32 v19, 0x3f317217, v9
	v_fma_f32 v19, v9, s44, -v19
	v_fmac_f32_e32 v19, 0x3377d1cf, v9
	v_fmac_f32_e32 v19, 0x3f317217, v9
	v_mov_b32_e32 v9, v19
	v_sub_f32_e32 v8, v8, v9
	v_add_f32_e32 v8, v8, v71
	v_max_f32_e32 v9, v87, v8
	v_sub_f32_e32 v8, v70, v8
	v_mul_f32_e64 v8, |v8|, s43
	v_exp_f32_e32 v8, v8
	s_nop 0
	v_add_f32_e32 v8, 1.0, v8
	v_log_f32_e32 v8, v8
	s_nop 0
	v_mul_f32_e32 v19, 0x3f317217, v8
	v_fma_f32 v19, v8, s44, -v19
	v_fmac_f32_e32 v19, 0x3377d1cf, v8
	v_fmac_f32_e32 v19, 0x3f317217, v8
	v_mov_b32_e32 v8, v19
	v_add_f32_e32 v19, v9, v8
	v_mul_f32_e64 v9, |v10|, s43
	v_exp_f32_e32 v9, v9
	v_max_f32_e32 v8, v10, v10
	v_min_f32_e32 v8, 0, v8
	v_add_f32_e32 v9, 1.0, v9
	v_log_f32_e32 v9, v9
	s_nop 0
	v_mul_f32_e32 v10, 0x3f317217, v9
	v_fma_f32 v10, v9, s44, -v10
	v_fmac_f32_e32 v10, 0x3377d1cf, v9
	v_fmac_f32_e32 v10, 0x3f317217, v9
	v_mov_b32_e32 v9, v10
	v_sub_f32_e32 v8, v8, v9
	v_add_f32_e32 v8, v8, v65
	v_max_f32_e32 v9, v58, v8
	v_sub_f32_e32 v8, v64, v8
	v_mul_f32_e64 v8, |v8|, s43
	v_exp_f32_e32 v8, v8
	s_nop 0
	v_add_f32_e32 v8, 1.0, v8
	v_log_f32_e32 v8, v8
	s_nop 0
	v_mul_f32_e32 v10, 0x3f317217, v8
	v_fma_f32 v10, v8, s44, -v10
	v_fmac_f32_e32 v10, 0x3377d1cf, v8
	v_fmac_f32_e32 v10, 0x3f317217, v8
	v_mov_b32_e32 v8, v10
	v_add_f32_e32 v20, v9, v8
	v_mul_f32_e64 v9, |v11|, s43
	v_exp_f32_e32 v9, v9
	v_max_f32_e32 v8, v11, v11
	v_min_f32_e32 v8, 0, v8
	v_add_f32_e32 v9, 1.0, v9
	v_log_f32_e32 v9, v9
	s_nop 0
	v_mul_f32_e32 v10, 0x3f317217, v9
	v_fma_f32 v10, v9, s44, -v10
	v_fmac_f32_e32 v10, 0x3377d1cf, v9
	v_fmac_f32_e32 v10, 0x3f317217, v9
	v_mov_b32_e32 v9, v10
	v_sub_f32_e32 v8, v8, v9
	v_add_f32_e32 v8, v8, v67
	v_max_f32_e32 v9, v59, v8
	v_sub_f32_e32 v8, v66, v8
	v_mul_f32_e64 v8, |v8|, s43
	v_exp_f32_e32 v8, v8
	s_nop 0
	v_add_f32_e32 v8, 1.0, v8
	v_log_f32_e32 v8, v8
	s_nop 0
	v_mul_f32_e32 v10, 0x3f317217, v8
	v_fma_f32 v10, v8, s44, -v10
	v_fmac_f32_e32 v10, 0x3377d1cf, v8
	v_fmac_f32_e32 v10, 0x3f317217, v8
	v_mov_b32_e32 v8, v10
	v_add_f32_e32 v11, v9, v8
	v_cvt_pk_f16_f32 v8, v12, v13
	v_add_co_u32_e32 v12, vcc, s20, v16
	v_cvt_pk_f16_f32 v9, v14, v15
	v_cvt_pk_f16_f32 v10, v18, v19
	v_cvt_pk_f16_f32 v11, v20, v11
	v_addc_co_u32_e32 v13, vcc, 0, v17, vcc
	global_store_dwordx4 v[12:13], v[8:11], off offset:256
	s_nop 1
	v_max_f32_e32 v10, v4, v4
	v_mul_f32_e64 v4, |v4|, s43
	v_exp_f32_e32 v4, v4
	v_min_f32_e32 v10, 0, v10
	v_lshl_add_u64 v[8:9], s[90:91], 0, v[80:81]
	v_lshl_add_u64 v[8:9], v[8:9], 0, v[208:209]
	v_add_f32_e32 v4, 1.0, v4
	v_log_f32_e32 v4, v4
	s_nop 0
	v_mul_f32_e32 v11, 0x3f317217, v4
	v_fma_f32 v11, v4, s44, -v11
	v_fmac_f32_e32 v11, 0x3377d1cf, v4
	v_fmac_f32_e32 v11, 0x3f317217, v4
	v_mov_b32_e32 v4, v11
	v_sub_f32_e32 v4, v10, v4
	v_add_f32_e32 v4, v4, v77
	v_max_f32_e32 v10, v60, v4
	v_sub_f32_e32 v4, v76, v4
	v_mul_f32_e64 v4, |v4|, s43
	v_exp_f32_e32 v4, v4
	s_nop 0
	v_add_f32_e32 v4, 1.0, v4
	v_log_f32_e32 v4, v4
	s_nop 0
	v_mul_f32_e32 v11, 0x3f317217, v4
	v_fma_f32 v11, v4, s44, -v11
	v_fmac_f32_e32 v11, 0x3377d1cf, v4
	v_fmac_f32_e32 v11, 0x3f317217, v4
	v_mov_b32_e32 v4, v11
	v_add_f32_e32 v4, v10, v4
	v_max_f32_e32 v10, v5, v5
	v_mul_f32_e64 v5, |v5|, s43
	v_exp_f32_e32 v5, v5
	v_min_f32_e32 v10, 0, v10
	v_add_f32_e32 v5, 1.0, v5
	v_log_f32_e32 v5, v5
	s_nop 0
	v_mul_f32_e32 v11, 0x3f317217, v5
	v_fma_f32 v11, v5, s44, -v11
	v_fmac_f32_e32 v11, 0x3377d1cf, v5
	v_fmac_f32_e32 v11, 0x3f317217, v5
	v_mov_b32_e32 v5, v11
	v_sub_f32_e32 v5, v10, v5
	v_add_f32_e32 v5, v5, v79
	v_max_f32_e32 v10, v61, v5
	v_sub_f32_e32 v5, v78, v5
	v_mul_f32_e64 v5, |v5|, s43
	v_exp_f32_e32 v5, v5
	s_nop 0
	v_add_f32_e32 v5, 1.0, v5
	v_log_f32_e32 v5, v5
	s_nop 0
	v_mul_f32_e32 v11, 0x3f317217, v5
	v_fma_f32 v11, v5, s44, -v11
	v_fmac_f32_e32 v11, 0x3377d1cf, v5
	v_fmac_f32_e32 v11, 0x3f317217, v5
	v_mov_b32_e32 v5, v11
	v_add_f32_e32 v5, v10, v5
	v_max_f32_e32 v10, v6, v6
	v_mul_f32_e64 v6, |v6|, s43
	v_exp_f32_e32 v6, v6
	v_min_f32_e32 v10, 0, v10
	v_add_f32_e32 v6, 1.0, v6
	v_log_f32_e32 v6, v6
	s_nop 0
	v_mul_f32_e32 v11, 0x3f317217, v6
	v_fma_f32 v11, v6, s44, -v11
	v_fmac_f32_e32 v11, 0x3377d1cf, v6
	v_fmac_f32_e32 v11, 0x3f317217, v6
	v_mov_b32_e32 v6, v11
	v_sub_f32_e32 v6, v10, v6
	v_add_f32_e32 v6, v6, v73
	v_max_f32_e32 v10, v62, v6
	v_sub_f32_e32 v6, v72, v6
	v_mul_f32_e64 v6, |v6|, s43
	v_exp_f32_e32 v6, v6
	s_nop 0
	v_add_f32_e32 v6, 1.0, v6
	v_log_f32_e32 v6, v6
	s_nop 0
	v_mul_f32_e32 v11, 0x3f317217, v6
	v_fma_f32 v11, v6, s44, -v11
	v_fmac_f32_e32 v11, 0x3377d1cf, v6
	v_fmac_f32_e32 v11, 0x3f317217, v6
	v_mov_b32_e32 v6, v11
	v_add_f32_e32 v6, v10, v6
	v_max_f32_e32 v10, v7, v7
	v_mul_f32_e64 v7, |v7|, s43
	v_exp_f32_e32 v7, v7
	v_min_f32_e32 v10, 0, v10
	v_add_f32_e32 v7, 1.0, v7
	v_log_f32_e32 v7, v7
	s_nop 0
	v_mul_f32_e32 v11, 0x3f317217, v7
	v_fma_f32 v11, v7, s44, -v11
	v_fmac_f32_e32 v11, 0x3377d1cf, v7
	v_fmac_f32_e32 v11, 0x3f317217, v7
	v_mov_b32_e32 v7, v11
	v_sub_f32_e32 v7, v10, v7
	v_add_f32_e32 v7, v7, v75
	v_max_f32_e32 v10, v63, v7
	v_sub_f32_e32 v7, v74, v7
	v_mul_f32_e64 v7, |v7|, s43
	v_exp_f32_e32 v7, v7
	s_nop 0
	v_add_f32_e32 v7, 1.0, v7
	v_log_f32_e32 v7, v7
	s_nop 0
	v_mul_f32_e32 v11, 0x3f317217, v7
	v_fma_f32 v11, v7, s44, -v11
	v_fmac_f32_e32 v11, 0x3377d1cf, v7
	v_fmac_f32_e32 v11, 0x3f317217, v7
	v_mov_b32_e32 v7, v11
	v_add_f32_e32 v7, v10, v7
	v_max_f32_e32 v10, v0, v0
	v_mul_f32_e64 v0, |v0|, s43
	v_exp_f32_e32 v0, v0
	v_min_f32_e32 v10, 0, v10
	v_add_f32_e32 v0, 1.0, v0
	v_log_f32_e32 v0, v0
	s_nop 0
	v_mul_f32_e32 v11, 0x3f317217, v0
	v_fma_f32 v11, v0, s44, -v11
	v_fmac_f32_e32 v11, 0x3377d1cf, v0
	v_fmac_f32_e32 v11, 0x3f317217, v0
	v_mov_b32_e32 v0, v11
	v_sub_f32_e32 v0, v10, v0
	v_add_f32_e32 v0, v0, v69
	v_max_f32_e32 v10, v86, v0
	v_sub_f32_e32 v0, v68, v0
	v_mul_f32_e64 v0, |v0|, s43
	v_exp_f32_e32 v0, v0
	s_nop 0
	v_add_f32_e32 v0, 1.0, v0
	v_log_f32_e32 v0, v0
	s_nop 0
	v_mul_f32_e32 v11, 0x3f317217, v0
	v_fma_f32 v11, v0, s44, -v11
	v_fmac_f32_e32 v11, 0x3377d1cf, v0
	v_fmac_f32_e32 v11, 0x3f317217, v0
	v_mov_b32_e32 v0, v11
	v_add_f32_e32 v10, v10, v0
	v_max_f32_e32 v0, v1, v1
	v_mul_f32_e64 v1, |v1|, s43
	v_exp_f32_e32 v1, v1
	v_min_f32_e32 v0, 0, v0
	v_add_f32_e32 v1, 1.0, v1
	v_log_f32_e32 v1, v1
	s_nop 0
	v_mul_f32_e32 v11, 0x3f317217, v1
	v_fma_f32 v11, v1, s44, -v11
	v_fmac_f32_e32 v11, 0x3377d1cf, v1
	v_fmac_f32_e32 v11, 0x3f317217, v1
	v_mov_b32_e32 v1, v11
	v_sub_f32_e32 v0, v0, v1
	v_add_f32_e32 v0, v0, v71
	v_max_f32_e32 v1, v87, v0
	v_sub_f32_e32 v0, v70, v0
	v_mul_f32_e64 v0, |v0|, s43
	v_exp_f32_e32 v0, v0
	s_nop 0
	v_add_f32_e32 v0, 1.0, v0
	v_log_f32_e32 v0, v0
	s_nop 0
	v_mul_f32_e32 v11, 0x3f317217, v0
	v_fma_f32 v11, v0, s44, -v11
	v_fmac_f32_e32 v11, 0x3377d1cf, v0
	v_fmac_f32_e32 v11, 0x3f317217, v0
	v_mov_b32_e32 v0, v11
	v_add_f32_e32 v11, v1, v0
	v_mul_f32_e64 v1, |v2|, s43
	v_exp_f32_e32 v1, v1
	v_max_f32_e32 v0, v2, v2
	v_min_f32_e32 v0, 0, v0
	v_add_f32_e32 v1, 1.0, v1
	v_log_f32_e32 v1, v1
	s_nop 0
	v_mul_f32_e32 v2, 0x3f317217, v1
	v_fma_f32 v2, v1, s44, -v2
	v_fmac_f32_e32 v2, 0x3377d1cf, v1
	v_fmac_f32_e32 v2, 0x3f317217, v1
	v_mov_b32_e32 v1, v2
	v_sub_f32_e32 v0, v0, v1
	v_add_f32_e32 v0, v0, v65
	v_max_f32_e32 v1, v58, v0
	v_sub_f32_e32 v0, v64, v0
	v_mul_f32_e64 v0, |v0|, s43
	v_exp_f32_e32 v0, v0
	s_nop 0
	v_add_f32_e32 v0, 1.0, v0
	v_log_f32_e32 v0, v0
	s_nop 0
	v_mul_f32_e32 v2, 0x3f317217, v0
	v_fma_f32 v2, v0, s44, -v2
	v_fmac_f32_e32 v2, 0x3377d1cf, v0
	v_fmac_f32_e32 v2, 0x3f317217, v0
	v_mov_b32_e32 v0, v2
	v_add_f32_e32 v12, v1, v0
	v_mul_f32_e64 v1, |v3|, s43
	v_exp_f32_e32 v1, v1
	v_max_f32_e32 v0, v3, v3
	v_min_f32_e32 v0, 0, v0
	v_add_f32_e32 v1, 1.0, v1
	v_log_f32_e32 v1, v1
	s_nop 0
	v_mul_f32_e32 v2, 0x3f317217, v1
	v_fma_f32 v2, v1, s44, -v2
	v_fmac_f32_e32 v2, 0x3377d1cf, v1
	v_fmac_f32_e32 v2, 0x3f317217, v1
	v_mov_b32_e32 v1, v2
	v_sub_f32_e32 v0, v0, v1
	v_add_f32_e32 v0, v0, v67
	v_max_f32_e32 v1, v59, v0
	v_sub_f32_e32 v0, v66, v0
	v_mul_f32_e64 v0, |v0|, s43
	v_exp_f32_e32 v0, v0
	s_nop 0
	v_add_f32_e32 v0, 1.0, v0
	v_log_f32_e32 v0, v0
	s_nop 0
	v_mul_f32_e32 v2, 0x3f317217, v0
	v_fma_f32 v2, v0, s44, -v2
	v_fmac_f32_e32 v2, 0x3377d1cf, v0
	v_fmac_f32_e32 v2, 0x3f317217, v0
	v_mov_b32_e32 v0, v2
	v_add_f32_e32 v3, v1, v0
	v_cvt_pk_f16_f32 v0, v4, v5
	v_add_co_u32_e32 v4, vcc, 0xbc00000, v8
	v_cvt_pk_f16_f32 v1, v6, v7
	v_cvt_pk_f16_f32 v2, v10, v11
	v_cvt_pk_f16_f32 v3, v12, v3
	v_addc_co_u32_e32 v5, vcc, 0, v9, vcc
	global_store_dwordx4 v[4:5], v[0:3], off offset:256
	s_andn2_b64 vcc, exec, s[8:9]
	s_mov_b64 s[4:5], -1
	s_cbranch_vccnz .LBB0_380
